# first K-tile fragment reads issued at the tile-loop header, ahead of the next-tile index arithmetic
# speedup vs baseline: 1.0139x; 1.0009x over previous
; #define PG8_STAGE(bufoff, gbase, voff) do { _Pragma("unroll") for (int _i = 0; _i < 2; ++_i) { \
;         const unsigned _m0 = ldsb + (unsigned)((bufoff) + _i * 8192); const char* _gb = (const char*)(gbase); \
;         asm volatile("s_mov_b32 m0, %0\n\ts_nop 0\n\tglobal_load_lds_dwordx4 %1, %2" :: "s"(_m0), "v"((voff)[_i]), "s"(_gb) : "m0", "memory"); } } while (0)
; #define PG8_LDA(dst, b, h) do { _Pragma("unroll") for (int m = 0; m < 4; ++m) _Pragma("unroll") for (int k = 0; k < 2; ++k) dst[m][k] = *(const LAS bf16x8*)(lds + PG8_SA(b, h) + aoff + m * 2048 + k * 1024); } while (0)
; #define PG8_LDB(dst, b, h) do { _Pragma("unroll") for (int n = 0; n < 2; ++n) _Pragma("unroll") for (int k = 0; k < 2; ++k) dst[n][k] = *(const LAS bf16x8*)(lds + PG8_SB(b, h) + boff + n * 2048 + k * 1024); } while (0)
; #define PG8_SCHED __builtin_amdgcn_sched_barrier(0)
;     __device__ bool next(int i, Unit& u) const {
;         const long L = (long)i * G + c; if (L >= nwg) return false;
;         int wgid = (int)L; { const int q = nwg / NXCD, r = nwg % NXCD, xcd = wgid % NXCD, off = wgid / NXCD; wgid = (xcd < r ? xcd * (q + 1) : r * (q + 1) + (xcd - r) * q) + off; }
;         const int nig = WGM * nN, gid = wgid / nig, fm = gid * WGM, gsz = (nM - fm) < WGM ? (nM - fm) : WGM;
;         u.pm = fm + ((wgid % nig) % gsz); u.pn = (wgid % nig) / gsz; return true;
; template <class Epi, bool ALIGN_EPI>
; __device__ __forceinline__ void gemm_phase(LAS unsigned char* lds, const Gemm g, const StaticOrder& S, const Epi& E) {
;     ...
;         const bool has_next = S.next(ui + 1, nxt);
;         const char* nA = has_next ? (const char*)g.A + (size_t)nxt.pm * tstepA + (size_t)nxt.pn * g.a_pn_off * 2 + (size_t)(nxt.pm >> 4) * g.a_adj : cA; const char* nB = has_next ? (const char*)g.Bt + (size_t)nxt.pn * tstepB : cB;
;         for (int t = 0; t < nt; t += 2) {
;             const bool last = (t == nt - 2);
;             const char* a1 = cA + (size_t)(t + 1) * kstep;
;             const char* a2 = last ? nA : cA + (size_t)(t + 2) * kstep; const char* b2 = last ? nB : cB + (size_t)(t + 2) * kstep;
;             const char* a3 = a2 + kstep; const char* b3 = b2 + kstep;
;             PG8_LDB(B0, 0, 0); PG8_LDB(B1, 0, 1); PG8_SCHED; PG8_LDA(At, 0, 0); PG8_STAGE(PG8_SA(1, 1), a1 + hstepA, voffA);
.LBB0_140:
	v_add_u32_e32 v132, 0x10000, v244
	v_add_u32_e32 v152, 0x14000, v244
	ds_read_b128 v[108:111], v132
	ds_read_b128 v[120:123], v132 offset:1024
	ds_read_b128 v[128:131], v132 offset:2048
	ds_read_b128 v[132:135], v132 offset:3072
	ds_read_b128 v[136:139], v152
	ds_read_b128 v[144:147], v152 offset:1024
	ds_read_b128 v[148:151], v152 offset:2048
	ds_read_b128 v[152:155], v152 offset:3072
	ds_read_b128 v[156:159], v245
	ds_read_b128 v[160:163], v245 offset:1024
	ds_read_b128 v[164:167], v245 offset:2048
	ds_read_b128 v[176:179], v245 offset:3072
	ds_read_b128 v[180:183], v245 offset:4096
	ds_read_b128 v[184:187], v245 offset:5120
	ds_read_b128 v[188:191], v245 offset:6144
	ds_read_b128 v[202:205], v245 offset:7168
	s_add_i32 s80, s80, 1
	s_mul_i32 s0, s80, s96
	s_mul_hi_u32 s1, s80, s87
	s_add_i32 s1, s1, s0
	s_mul_i32 s0, s80, s87
	s_add_u32 s4, s0, s16
	s_addc_u32 s5, s1, s97
	v_cmp_gt_i64_e32 vcc, s[4:5], v[198:199]
	v_cmp_lt_i64_e64 s[0:1], s[4:5], v[196:197]
	s_cbranch_vccnz .LBB0_146
	s_ashr_i32 s5, s4, 31
	s_lshr_b32 s5, s5, 29
	s_add_i32 s8, s4, s5
	s_and_b32 s5, s8, -8
	s_sub_i32 s9, s4, s5
	s_cmp_gt_i32 s9, -1
	s_mov_b64 s[4:5], -1
	s_cbranch_scc0 .LBB0_143
	s_lshl_b32 s14, s9, 6
	s_mov_b64 s[4:5], 0

; #define PG8_STAGE(bufoff, gbase, voff) do { _Pragma("unroll") for (int _i = 0; _i < 2; ++_i) { \
;         const unsigned _m0 = ldsb + (unsigned)((bufoff) + _i * 8192); const char* _gb = (const char*)(gbase); \
;         asm volatile("s_mov_b32 m0, %0\n\ts_nop 0\n\tglobal_load_lds_dwordx4 %1, %2" :: "s"(_m0), "v"((voff)[_i]), "s"(_gb) : "m0", "memory"); } } while (0)
; #define PG8_LDA(dst, b, h) do { _Pragma("unroll") for (int m = 0; m < 4; ++m) _Pragma("unroll") for (int k = 0; k < 2; ++k) dst[m][k] = *(const LAS bf16x8*)(lds + PG8_SA(b, h) + aoff + m * 2048 + k * 1024); } while (0)
; #define PG8_LDB(dst, b, h) do { _Pragma("unroll") for (int n = 0; n < 2; ++n) _Pragma("unroll") for (int k = 0; k < 2; ++k) dst[n][k] = *(const LAS bf16x8*)(lds + PG8_SB(b, h) + boff + n * 2048 + k * 1024); } while (0)
; #define PG8_MMA(ai, bj, At, Bt) do { __builtin_amdgcn_s_setprio(1); _Pragma("unroll") for (int m = 0; m < 4; ++m) _Pragma("unroll") for (int n = 0; n < 2; ++n) _Pragma("unroll") for (int k = 0; k < 2; ++k) \
;         acc[ai][bj][m][n] = __builtin_amdgcn_mfma_f32_16x16x32_bf16(Bt[n][k], At[m][k], acc[ai][bj][m][n], 0, 0, 0); __builtin_amdgcn_s_setprio(0); } while (0)
; #define PG8_WAIT_V(n) asm volatile("s_waitcnt vmcnt(" #n ")" ::: "memory")
; #define PG8_WAIT_L(n) asm volatile("s_waitcnt lgkmcnt(" #n ")" ::: "memory")
; template <class Epi, bool ALIGN_EPI>
; __device__ __forceinline__ void gemm_phase(LAS unsigned char* lds, const Gemm g, const StaticOrder& S, const Epi& E) {
;     ...
;         for (int t = 0; t < nt; t += 2) {
;             const bool last = (t == nt - 2);
;             const char* a1 = cA + (size_t)(t + 1) * kstep;
;             const char* a2 = last ? nA : cA + (size_t)(t + 2) * kstep; const char* b2 = last ? nB : cB + (size_t)(t + 2) * kstep;
;             const char* a3 = a2 + kstep; const char* b3 = b2 + kstep;
;             PG8_LDB(B0, 0, 0); PG8_LDB(B1, 0, 1); PG8_SCHED; PG8_LDA(At, 0, 0); PG8_STAGE(PG8_SA(1, 1), a1 + hstepA, voffA);
;             PG8_WAIT_V(8); PG8_WAIT_L(0); PG8_BAR; PG8_MMA(0, 0, At, B0); PG8_MMA(0, 1, At, B1); PG8_BAR; PG8_SCHED;
;             PG8_LDA(At, 0, 1); PG8_STAGE(PG8_SB(0, 0), b2, voffB); PG8_STAGE(PG8_SB(0, 1), b2 + hstepB, voffB); PG8_STAGE(PG8_SA(0, 0), a2, voffA);
;             PG8_WAIT_V(8); PG8_WAIT_L(0); PG8_BAR; PG8_MMA(1, 0, At, B0); PG8_MMA(1, 1, At, B1); PG8_BAR; PG8_SCHED;
.LBB0_150:
	s_add_u32 s4, s48, 0x100
	s_addc_u32 s5, s49, 0
	s_add_u32 s37, s54, 0x100
	s_addc_u32 s44, s55, 0
	s_mov_b32 s45, 0
	s_waitcnt lgkmcnt(0)
	s_add_i32 s51, s45, 2
	s_cmp_eq_u32 s67, s45
	s_cselect_b32 s56, s0, s37
	s_cselect_b32 s57, s1, s44
	s_cselect_b32 s54, s94, s4
	s_cselect_b32 s55, s95, s5
	s_add_u32 s48, s56, 0x80
	s_addc_u32 s49, s57, 0
	s_add_u32 s45, s37, s15
	s_addc_u32 s59, s44, 0
	s_add_u32 s58, s45, 0xffffff80
	s_addc_u32 s59, s59, -1
	s_mov_b32 m0, s68
	s_nop 0
	global_load_lds_dwordx4 v0, s[58:59]
	s_nop 0
	s_mov_b32 m0, s85
	s_nop 0
	global_load_lds_dwordx4 v240, s[58:59]
	s_waitcnt vmcnt(8)
	s_waitcnt lgkmcnt(0)
	s_barrier
	s_setprio 1
	s_waitcnt lgkmcnt(0)
	v_mfma_f32_16x16x32_bf16 v[172:175], v[108:111], v[156:159], 0
	v_mfma_f32_16x16x32_bf16 v[172:175], v[120:123], v[160:163], v[172:175]
	v_mfma_f32_16x16x32_bf16 v[168:171], v[128:131], v[156:159], 0
	v_mfma_f32_16x16x32_bf16 v[168:171], v[132:135], v[160:163], v[168:171]
	v_mfma_f32_16x16x32_bf16 v[140:143], v[136:139], v[156:159], 0
	v_mfma_f32_16x16x32_bf16 v[140:143], v[144:147], v[160:163], v[140:143]
	v_mfma_f32_16x16x32_bf16 v[124:127], v[148:151], v[156:159], 0
	v_mfma_f32_16x16x32_bf16 v[124:127], v[152:155], v[160:163], v[124:127]
	v_mfma_f32_16x16x32_bf16 v[100:103], v[148:151], v[164:167], 0
	v_mfma_f32_16x16x32_bf16 v[100:103], v[152:155], v[176:179], v[100:103]
	v_mfma_f32_16x16x32_bf16 v[104:107], v[136:139], v[164:167], 0
	v_mfma_f32_16x16x32_bf16 v[104:107], v[144:147], v[176:179], v[104:107]
	v_mfma_f32_16x16x32_bf16 v[112:115], v[128:131], v[164:167], 0
	v_mfma_f32_16x16x32_bf16 v[112:115], v[132:135], v[176:179], v[112:115]
	v_mfma_f32_16x16x32_bf16 v[116:119], v[108:111], v[164:167], 0
	v_mfma_f32_16x16x32_bf16 v[116:119], v[120:123], v[176:179], v[116:119]
	v_mfma_f32_16x16x32_bf16 v[96:99], v[108:111], v[180:183], 0
	v_mfma_f32_16x16x32_bf16 v[96:99], v[120:123], v[184:187], v[96:99]
	v_mfma_f32_16x16x32_bf16 v[92:95], v[128:131], v[180:183], 0
	v_mfma_f32_16x16x32_bf16 v[92:95], v[132:135], v[184:187], v[92:95]
	v_mfma_f32_16x16x32_bf16 v[88:91], v[136:139], v[180:183], 0
	v_mfma_f32_16x16x32_bf16 v[88:91], v[144:147], v[184:187], v[88:91]
	v_mfma_f32_16x16x32_bf16 v[84:87], v[148:151], v[180:183], 0
	v_mfma_f32_16x16x32_bf16 v[84:87], v[152:155], v[184:187], v[84:87]
	v_mfma_f32_16x16x32_bf16 v[68:71], v[148:151], v[188:191], 0
	v_mfma_f32_16x16x32_bf16 v[68:71], v[152:155], v[202:205], v[68:71]
	v_mfma_f32_16x16x32_bf16 v[72:75], v[136:139], v[188:191], 0
	v_mfma_f32_16x16x32_bf16 v[72:75], v[144:147], v[202:205], v[72:75]
	v_mfma_f32_16x16x32_bf16 v[76:79], v[128:131], v[188:191], 0
	v_mfma_f32_16x16x32_bf16 v[76:79], v[132:135], v[202:205], v[76:79]
	v_mfma_f32_16x16x32_bf16 v[80:83], v[108:111], v[188:191], 0
	v_mfma_f32_16x16x32_bf16 v[80:83], v[120:123], v[202:205], v[80:83]
	s_setprio 0
	s_barrier
	ds_read_b128 v[156:159], v245 offset:16384
	ds_read_b128 v[160:163], v245 offset:17408
	ds_read_b128 v[164:167], v245 offset:18432
	ds_read_b128 v[176:179], v245 offset:19456
	ds_read_b128 v[180:183], v245 offset:20480
	ds_read_b128 v[184:187], v245 offset:21504
	ds_read_b128 v[188:191], v245 offset:22528
	ds_read_b128 v[202:205], v245 offset:23552
	s_mov_b32 m0, s27
	s_nop 0
	global_load_lds_dwordx4 v195, s[54:55]
	s_add_u32 s58, s54, s15
	s_mov_b32 m0, s28
	s_nop 0
	global_load_lds_dwordx4 v241, s[54:55]
	s_addc_u32 s59, s55, 0
	s_mov_b32 m0, s29
	s_nop 0
	global_load_lds_dwordx4 v195, s[58:59]
	s_nop 0
	s_mov_b32 m0, s30
	s_nop 0
	global_load_lds_dwordx4 v241, s[58:59]
	s_nop 0
	s_mov_b32 m0, s26
	s_nop 0
	global_load_lds_dwordx4 v0, s[56:57]
	s_nop 0
	s_mov_b32 m0, s31
	s_nop 0
	global_load_lds_dwordx4 v240, s[56:57]
	s_waitcnt vmcnt(8)
	s_waitcnt lgkmcnt(0)
	s_barrier
	s_setprio 1
	s_waitcnt lgkmcnt(0)
	v_mfma_f32_16x16x32_bf16 v[64:67], v[108:111], v[156:159], 0
	v_mfma_f32_16x16x32_bf16 v[64:67], v[120:123], v[160:163], v[64:67]
	v_mfma_f32_16x16x32_bf16 v[60:63], v[128:131], v[156:159], 0
	v_mfma_f32_16x16x32_bf16 v[60:63], v[132:135], v[160:163], v[60:63]
	v_mfma_f32_16x16x32_bf16 v[56:59], v[136:139], v[156:159], 0
	v_mfma_f32_16x16x32_bf16 v[56:59], v[144:147], v[160:163], v[56:59]
	v_mfma_f32_16x16x32_bf16 v[52:55], v[148:151], v[156:159], 0
	v_mfma_f32_16x16x32_bf16 v[52:55], v[152:155], v[160:163], v[52:55]
	v_mfma_f32_16x16x32_bf16 v[36:39], v[148:151], v[164:167], 0
	v_mfma_f32_16x16x32_bf16 v[36:39], v[152:155], v[176:179], v[36:39]
	v_mfma_f32_16x16x32_bf16 v[40:43], v[136:139], v[164:167], 0
	v_mfma_f32_16x16x32_bf16 v[40:43], v[144:147], v[176:179], v[40:43]
	v_mfma_f32_16x16x32_bf16 v[44:47], v[128:131], v[164:167], 0
	v_mfma_f32_16x16x32_bf16 v[44:47], v[132:135], v[176:179], v[44:47]
	v_mfma_f32_16x16x32_bf16 v[48:51], v[108:111], v[164:167], 0
	v_mfma_f32_16x16x32_bf16 v[48:51], v[120:123], v[176:179], v[48:51]
	v_mfma_f32_16x16x32_bf16 v[32:35], v[108:111], v[180:183], 0
	v_mfma_f32_16x16x32_bf16 v[32:35], v[120:123], v[184:187], v[32:35]
	v_mfma_f32_16x16x32_bf16 v[28:31], v[128:131], v[180:183], 0
	v_mfma_f32_16x16x32_bf16 v[28:31], v[132:135], v[184:187], v[28:31]
	v_mfma_f32_16x16x32_bf16 v[24:27], v[136:139], v[180:183], 0
	v_mfma_f32_16x16x32_bf16 v[24:27], v[144:147], v[184:187], v[24:27]
	v_mfma_f32_16x16x32_bf16 v[20:23], v[148:151], v[180:183], 0
	v_mfma_f32_16x16x32_bf16 v[20:23], v[152:155], v[184:187], v[20:23]
	v_mfma_f32_16x16x32_bf16 v[4:7], v[148:151], v[188:191], 0
	v_mfma_f32_16x16x32_bf16 v[4:7], v[152:155], v[202:205], v[4:7]
	v_mfma_f32_16x16x32_bf16 v[8:11], v[136:139], v[188:191], 0
	v_mfma_f32_16x16x32_bf16 v[8:11], v[144:147], v[202:205], v[8:11]
	v_mfma_f32_16x16x32_bf16 v[12:15], v[128:131], v[188:191], 0
	v_mfma_f32_16x16x32_bf16 v[12:15], v[132:135], v[202:205], v[12:15]
	v_mfma_f32_16x16x32_bf16 v[16:19], v[108:111], v[188:191], 0
	v_mfma_f32_16x16x32_bf16 v[16:19], v[120:123], v[202:205], v[16:19]
	s_setprio 0
	s_barrier
; #define PG8_STAGE(bufoff, gbase, voff) do { _Pragma("unroll") for (int _i = 0; _i < 2; ++_i) { \
;         const unsigned _m0 = ldsb + (unsigned)((bufoff) + _i * 8192); const char* _gb = (const char*)(gbase); \
;         asm volatile("s_mov_b32 m0, %0\n\ts_nop 0\n\tglobal_load_lds_dwordx4 %1, %2" :: "s"(_m0), "v"((voff)[_i]), "s"(_gb) : "m0", "memory"); } } while (0)
; #define PG8_LDA(dst, b, h) do { _Pragma("unroll") for (int m = 0; m < 4; ++m) _Pragma("unroll") for (int k = 0; k < 2; ++k) dst[m][k] = *(const LAS bf16x8*)(lds + PG8_SA(b, h) + aoff + m * 2048 + k * 1024); } while (0)
; #define PG8_LDB(dst, b, h) do { _Pragma("unroll") for (int n = 0; n < 2; ++n) _Pragma("unroll") for (int k = 0; k < 2; ++k) dst[n][k] = *(const LAS bf16x8*)(lds + PG8_SB(b, h) + boff + n * 2048 + k * 1024); } while (0)
; #define PG8_MMA(ai, bj, At, Bt) do { __builtin_amdgcn_s_setprio(1); _Pragma("unroll") for (int m = 0; m < 4; ++m) _Pragma("unroll") for (int n = 0; n < 2; ++n) _Pragma("unroll") for (int k = 0; k < 2; ++k) \
;         acc[ai][bj][m][n] = __builtin_amdgcn_mfma_f32_16x16x32_bf16(Bt[n][k], At[m][k], acc[ai][bj][m][n], 0, 0, 0); __builtin_amdgcn_s_setprio(0); } while (0)
; #define PG8_WAIT_V(n) asm volatile("s_waitcnt vmcnt(" #n ")" ::: "memory")
; #define PG8_WAIT_L(n) asm volatile("s_waitcnt lgkmcnt(" #n ")" ::: "memory")
; #define PG8_BAR __builtin_amdgcn_s_barrier()
; #define PG8_SCHED __builtin_amdgcn_sched_barrier(0)
; template <class Epi, bool ALIGN_EPI>
; __device__ __forceinline__ void gemm_phase(LAS unsigned char* lds, const Gemm g, const StaticOrder& S, const Epi& E) {
;     ...
;             PG8_LDB(B0, 1, 0); PG8_LDB(B1, 1, 1); PG8_SCHED; PG8_LDA(At, 1, 0); PG8_STAGE(PG8_SA(0, 1), a2 + hstepA, voffA);
;             PG8_WAIT_V(8); PG8_WAIT_L(0); PG8_BAR; PG8_MMA(0, 0, At, B0); PG8_MMA(0, 1, At, B1); PG8_BAR; PG8_SCHED;
;             PG8_LDA(At, 1, 1); PG8_STAGE(PG8_SB(1, 0), b3, voffB); PG8_STAGE(PG8_SB(1, 1), b3 + hstepB, voffB); PG8_STAGE(PG8_SA(1, 0), a3, voffA);
;             PG8_WAIT_V(8); PG8_WAIT_L(0); PG8_BAR; PG8_MMA(1, 0, At, B0); PG8_MMA(1, 1, At, B1); PG8_BAR; PG8_SCHED;
;         }
	v_add_u32_e32 v132, 0x18000, v244
	v_add_u32_e32 v152, 0x1c000, v244
	ds_read_b128 v[108:111], v132
	ds_read_b128 v[120:123], v132 offset:1024
	ds_read_b128 v[128:131], v132 offset:2048
	ds_read_b128 v[132:135], v132 offset:3072
	ds_read_b128 v[136:139], v152
	ds_read_b128 v[144:147], v152 offset:1024
	ds_read_b128 v[148:151], v152 offset:2048
	ds_read_b128 v[152:155], v152 offset:3072
	ds_read_b128 v[156:159], v245 offset:32768
	ds_read_b128 v[160:163], v245 offset:33792
	ds_read_b128 v[164:167], v245 offset:34816
	ds_read_b128 v[176:179], v245 offset:35840
	ds_read_b128 v[180:183], v245 offset:36864
	ds_read_b128 v[184:187], v245 offset:37888
	ds_read_b128 v[188:191], v245 offset:38912
	ds_read_b128 v[202:205], v245 offset:39936
	s_add_u32 s56, s56, s15
	s_addc_u32 s57, s57, 0
	s_mov_b32 m0, s41
	s_nop 0
	global_load_lds_dwordx4 v0, s[56:57]
	s_nop 0
	s_mov_b32 m0, s42
	s_nop 0
	global_load_lds_dwordx4 v240, s[56:57]
	s_waitcnt vmcnt(8)
	s_waitcnt lgkmcnt(0)
	s_barrier
	s_setprio 1
	s_waitcnt lgkmcnt(0)
	v_mfma_f32_16x16x32_bf16 v[172:175], v[108:111], v[156:159], v[172:175]
	v_mfma_f32_16x16x32_bf16 v[172:175], v[120:123], v[160:163], v[172:175]
	v_mfma_f32_16x16x32_bf16 v[168:171], v[128:131], v[156:159], v[168:171]
	v_mfma_f32_16x16x32_bf16 v[168:171], v[132:135], v[160:163], v[168:171]
	v_mfma_f32_16x16x32_bf16 v[140:143], v[136:139], v[156:159], v[140:143]
	v_mfma_f32_16x16x32_bf16 v[140:143], v[144:147], v[160:163], v[140:143]
	v_mfma_f32_16x16x32_bf16 v[124:127], v[148:151], v[156:159], v[124:127]
	v_mfma_f32_16x16x32_bf16 v[124:127], v[152:155], v[160:163], v[124:127]
	v_mfma_f32_16x16x32_bf16 v[100:103], v[148:151], v[164:167], v[100:103]
	v_mfma_f32_16x16x32_bf16 v[100:103], v[152:155], v[176:179], v[100:103]
	v_mfma_f32_16x16x32_bf16 v[104:107], v[136:139], v[164:167], v[104:107]
	v_mfma_f32_16x16x32_bf16 v[104:107], v[144:147], v[176:179], v[104:107]
	v_mfma_f32_16x16x32_bf16 v[112:115], v[128:131], v[164:167], v[112:115]
	v_mfma_f32_16x16x32_bf16 v[112:115], v[132:135], v[176:179], v[112:115]
	v_mfma_f32_16x16x32_bf16 v[116:119], v[108:111], v[164:167], v[116:119]
	v_mfma_f32_16x16x32_bf16 v[116:119], v[120:123], v[176:179], v[116:119]
	v_mfma_f32_16x16x32_bf16 v[96:99], v[108:111], v[180:183], v[96:99]
	v_mfma_f32_16x16x32_bf16 v[96:99], v[120:123], v[184:187], v[96:99]
	v_mfma_f32_16x16x32_bf16 v[92:95], v[128:131], v[180:183], v[92:95]
	v_mfma_f32_16x16x32_bf16 v[92:95], v[132:135], v[184:187], v[92:95]
	v_mfma_f32_16x16x32_bf16 v[88:91], v[136:139], v[180:183], v[88:91]
	v_mfma_f32_16x16x32_bf16 v[88:91], v[144:147], v[184:187], v[88:91]
	v_mfma_f32_16x16x32_bf16 v[84:87], v[148:151], v[180:183], v[84:87]
	v_mfma_f32_16x16x32_bf16 v[84:87], v[152:155], v[184:187], v[84:87]
	v_mfma_f32_16x16x32_bf16 v[68:71], v[148:151], v[188:191], v[68:71]
	v_mfma_f32_16x16x32_bf16 v[68:71], v[152:155], v[202:205], v[68:71]
	v_mfma_f32_16x16x32_bf16 v[72:75], v[136:139], v[188:191], v[72:75]
	v_mfma_f32_16x16x32_bf16 v[72:75], v[144:147], v[202:205], v[72:75]
	v_mfma_f32_16x16x32_bf16 v[76:79], v[128:131], v[188:191], v[76:79]
	v_mfma_f32_16x16x32_bf16 v[76:79], v[132:135], v[202:205], v[76:79]
	v_mfma_f32_16x16x32_bf16 v[80:83], v[108:111], v[188:191], v[80:83]
	v_mfma_f32_16x16x32_bf16 v[80:83], v[120:123], v[202:205], v[80:83]
	s_setprio 0
	s_barrier
	ds_read_b128 v[156:159], v245 offset:49152
	ds_read_b128 v[160:163], v245 offset:50176
	ds_read_b128 v[164:167], v245 offset:51200
	ds_read_b128 v[176:179], v245 offset:52224
	ds_read_b128 v[180:183], v245 offset:53248
	ds_read_b128 v[184:187], v245 offset:54272
	ds_read_b128 v[188:191], v245 offset:55296
	ds_read_b128 v[202:205], v245 offset:56320
	s_add_u32 s54, s54, 0x80
	s_addc_u32 s55, s55, 0
	s_mov_b32 m0, s46
	s_nop 0
	global_load_lds_dwordx4 v195, s[54:55]
	s_nop 0
	s_mov_b32 m0, s50
	s_nop 0
	global_load_lds_dwordx4 v241, s[54:55]
	s_add_u32 s54, s58, 0x80
	s_addc_u32 s55, s59, 0
	s_mov_b32 m0, s61
	s_nop 0
	global_load_lds_dwordx4 v195, s[54:55]
	s_nop 0
	s_mov_b32 m0, s65
	s_nop 0
	global_load_lds_dwordx4 v241, s[54:55]
	s_nop 0
	s_mov_b32 m0, s53
	s_nop 0
	global_load_lds_dwordx4 v0, s[48:49]
	s_nop 0
	s_mov_b32 m0, s60
	s_nop 0
	global_load_lds_dwordx4 v240, s[48:49]
	s_waitcnt vmcnt(8)
	s_waitcnt lgkmcnt(0)
	s_barrier
	s_setprio 1
	s_waitcnt lgkmcnt(0)
	v_mfma_f32_16x16x32_bf16 v[64:67], v[108:111], v[156:159], v[64:67]
	v_mfma_f32_16x16x32_bf16 v[64:67], v[120:123], v[160:163], v[64:67]
	v_mfma_f32_16x16x32_bf16 v[60:63], v[128:131], v[156:159], v[60:63]
	v_mfma_f32_16x16x32_bf16 v[60:63], v[132:135], v[160:163], v[60:63]
	v_mfma_f32_16x16x32_bf16 v[56:59], v[136:139], v[156:159], v[56:59]
	v_mfma_f32_16x16x32_bf16 v[56:59], v[144:147], v[160:163], v[56:59]
	v_mfma_f32_16x16x32_bf16 v[52:55], v[148:151], v[156:159], v[52:55]
	v_mfma_f32_16x16x32_bf16 v[52:55], v[152:155], v[160:163], v[52:55]
	v_mfma_f32_16x16x32_bf16 v[36:39], v[148:151], v[164:167], v[36:39]
	v_mfma_f32_16x16x32_bf16 v[36:39], v[152:155], v[176:179], v[36:39]
	v_mfma_f32_16x16x32_bf16 v[40:43], v[136:139], v[164:167], v[40:43]
	v_mfma_f32_16x16x32_bf16 v[40:43], v[144:147], v[176:179], v[40:43]
	v_mfma_f32_16x16x32_bf16 v[44:47], v[128:131], v[164:167], v[44:47]
	v_mfma_f32_16x16x32_bf16 v[44:47], v[132:135], v[176:179], v[44:47]
	v_mfma_f32_16x16x32_bf16 v[48:51], v[108:111], v[164:167], v[48:51]
	v_mfma_f32_16x16x32_bf16 v[48:51], v[120:123], v[176:179], v[48:51]
	v_mfma_f32_16x16x32_bf16 v[32:35], v[108:111], v[180:183], v[32:35]
	v_mfma_f32_16x16x32_bf16 v[32:35], v[120:123], v[184:187], v[32:35]
	v_mfma_f32_16x16x32_bf16 v[28:31], v[128:131], v[180:183], v[28:31]
	v_mfma_f32_16x16x32_bf16 v[28:31], v[132:135], v[184:187], v[28:31]
	v_mfma_f32_16x16x32_bf16 v[24:27], v[136:139], v[180:183], v[24:27]
	v_mfma_f32_16x16x32_bf16 v[24:27], v[144:147], v[184:187], v[24:27]
	v_mfma_f32_16x16x32_bf16 v[20:23], v[148:151], v[180:183], v[20:23]
	v_mfma_f32_16x16x32_bf16 v[20:23], v[152:155], v[184:187], v[20:23]
	v_mfma_f32_16x16x32_bf16 v[4:7], v[148:151], v[188:191], v[4:7]
	v_mfma_f32_16x16x32_bf16 v[4:7], v[152:155], v[202:205], v[4:7]
	v_mfma_f32_16x16x32_bf16 v[8:11], v[136:139], v[188:191], v[8:11]
	v_mfma_f32_16x16x32_bf16 v[8:11], v[144:147], v[202:205], v[8:11]
	v_mfma_f32_16x16x32_bf16 v[12:15], v[128:131], v[188:191], v[12:15]
	v_mfma_f32_16x16x32_bf16 v[12:15], v[132:135], v[202:205], v[12:15]
	v_mfma_f32_16x16x32_bf16 v[16:19], v[108:111], v[188:191], v[16:19]
	v_mfma_f32_16x16x32_bf16 v[16:19], v[120:123], v[202:205], v[16:19]
	s_setprio 0
	s_barrier
	s_add_u32 s4, s4, 0x100
	s_addc_u32 s5, s5, 0
	s_add_u32 s37, s37, 0x100
	s_addc_u32 s44, s44, 0
	s_cmp_ge_u32 s51, s43
	s_mov_b32 s45, s51

; #define PG8_STAGE(bufoff, gbase, voff) do { _Pragma("unroll") for (int _i = 0; _i < 2; ++_i) { \
;         const unsigned _m0 = ldsb + (unsigned)((bufoff) + _i * 8192); const char* _gb = (const char*)(gbase); \
;         asm volatile("s_mov_b32 m0, %0\n\ts_nop 0\n\tglobal_load_lds_dwordx4 %1, %2" :: "s"(_m0), "v"((voff)[_i]), "s"(_gb) : "m0", "memory"); } } while (0)
; #define PG8_LDA(dst, b, h) do { _Pragma("unroll") for (int m = 0; m < 4; ++m) _Pragma("unroll") for (int k = 0; k < 2; ++k) dst[m][k] = *(const LAS bf16x8*)(lds + PG8_SA(b, h) + aoff + m * 2048 + k * 1024); } while (0)
; #define PG8_LDB(dst, b, h) do { _Pragma("unroll") for (int n = 0; n < 2; ++n) _Pragma("unroll") for (int k = 0; k < 2; ++k) dst[n][k] = *(const LAS bf16x8*)(lds + PG8_SB(b, h) + boff + n * 2048 + k * 1024); } while (0)
; #define PG8_SCHED __builtin_amdgcn_sched_barrier(0)
;     __device__ bool next(int i, Unit& u) const {
;         const long L = (long)i * G + c; if (L >= nwg) return false;
;         int wgid = (int)L; { const int q = nwg / NXCD, r = nwg % NXCD, xcd = wgid % NXCD, off = wgid / NXCD; wgid = (xcd < r ? xcd * (q + 1) : r * (q + 1) + (xcd - r) * q) + off; }
; template <class Epi, bool ALIGN_EPI>
; __device__ __forceinline__ void gemm_phase(LAS unsigned char* lds, const Gemm g, const StaticOrder& S, const Epi& E) {
;     ...
;             PG8_LDB(B0, 0, 0); PG8_LDB(B1, 0, 1); PG8_SCHED; PG8_LDA(At, 0, 0); PG8_STAGE(PG8_SA(1, 1), a1 + hstepA, voffA);
.LBB0_190:
	v_add_u32_e32 v142, 0x10000, v245
	v_add_u32_e32 v158, 0x14000, v245
	ds_read_b128 v[130:133], v142
	ds_read_b128 v[134:137], v142 offset:1024
	ds_read_b128 v[138:141], v142 offset:2048
	ds_read_b128 v[142:145], v142 offset:3072
	ds_read_b128 v[146:149], v158
	ds_read_b128 v[150:153], v158 offset:1024
	ds_read_b128 v[154:157], v158 offset:2048
	ds_read_b128 v[158:161], v158 offset:3072
	ds_read_b128 v[162:165], v246
	ds_read_b128 v[166:169], v246 offset:1024
	ds_read_b128 v[170:173], v246 offset:2048
	ds_read_b128 v[174:177], v246 offset:3072
	ds_read_b128 v[178:181], v246 offset:4096
	ds_read_b128 v[182:185], v246 offset:5120
	ds_read_b128 v[186:189], v246 offset:6144
	ds_read_b128 v[190:193], v246 offset:7168
	s_add_i32 s39, s39, 1
	s_mul_i32 s0, s39, s61
	s_mul_hi_u32 s1, s39, s87
	s_add_i32 s1, s1, s0
	s_mul_i32 s0, s39, s87
	v_readlane_b32 s4, v255, 8
	s_add_u32 s4, s0, s4
	s_addc_u32 s5, s1, s16
	v_cmp_gt_i64_e32 vcc, s[4:5], v[198:199]
	v_cmp_lt_i64_e64 s[0:1], s[4:5], v[196:197]
	s_cbranch_vccnz .LBB0_196
	s_ashr_i32 s5, s4, 31
	s_lshr_b32 s5, s5, 29
	s_add_i32 s8, s4, s5
	s_and_b32 s5, s8, -8
	s_sub_i32 s9, s4, s5
	s_cmp_gt_i32 s9, -1
	s_mov_b64 s[4:5], -1
	s_cbranch_scc0 .LBB0_193
	s_lshl_b32 s15, s9, 6
	s_mov_b64 s[4:5], 0

; #define PG8_STAGE(bufoff, gbase, voff) do { _Pragma("unroll") for (int _i = 0; _i < 2; ++_i) { \
;         const unsigned _m0 = ldsb + (unsigned)((bufoff) + _i * 8192); const char* _gb = (const char*)(gbase); \
;         asm volatile("s_mov_b32 m0, %0\n\ts_nop 0\n\tglobal_load_lds_dwordx4 %1, %2" :: "s"(_m0), "v"((voff)[_i]), "s"(_gb) : "m0", "memory"); } } while (0)
; #define PG8_LDA(dst, b, h) do { _Pragma("unroll") for (int m = 0; m < 4; ++m) _Pragma("unroll") for (int k = 0; k < 2; ++k) dst[m][k] = *(const LAS bf16x8*)(lds + PG8_SA(b, h) + aoff + m * 2048 + k * 1024); } while (0)
; #define PG8_LDB(dst, b, h) do { _Pragma("unroll") for (int n = 0; n < 2; ++n) _Pragma("unroll") for (int k = 0; k < 2; ++k) dst[n][k] = *(const LAS bf16x8*)(lds + PG8_SB(b, h) + boff + n * 2048 + k * 1024); } while (0)
; #define PG8_MMA(ai, bj, At, Bt) do { __builtin_amdgcn_s_setprio(1); _Pragma("unroll") for (int m = 0; m < 4; ++m) _Pragma("unroll") for (int n = 0; n < 2; ++n) _Pragma("unroll") for (int k = 0; k < 2; ++k) \
;         acc[ai][bj][m][n] = __builtin_amdgcn_mfma_f32_16x16x32_bf16(Bt[n][k], At[m][k], acc[ai][bj][m][n], 0, 0, 0); __builtin_amdgcn_s_setprio(0); } while (0)
; #define PG8_WAIT_V(n) asm volatile("s_waitcnt vmcnt(" #n ")" ::: "memory")
; #define PG8_WAIT_L(n) asm volatile("s_waitcnt lgkmcnt(" #n ")" ::: "memory")
; #define PG8_BAR __builtin_amdgcn_s_barrier()
; #define PG8_SCHED __builtin_amdgcn_sched_barrier(0)
; template <class Epi, bool ALIGN_EPI>
; __device__ __forceinline__ void gemm_phase(LAS unsigned char* lds, const Gemm g, const StaticOrder& S, const Epi& E) {
;     ...
;             const char* a1 = cA + (size_t)(t + 1) * kstep;
;             const char* a2 = last ? nA : cA + (size_t)(t + 2) * kstep; const char* b2 = last ? nB : cB + (size_t)(t + 2) * kstep;
;             const char* a3 = a2 + kstep; const char* b3 = b2 + kstep;
;             PG8_LDB(B0, 0, 0); PG8_LDB(B1, 0, 1); PG8_SCHED; PG8_LDA(At, 0, 0); PG8_STAGE(PG8_SA(1, 1), a1 + hstepA, voffA);
;             PG8_WAIT_V(8); PG8_WAIT_L(0); PG8_BAR; PG8_MMA(0, 0, At, B0); PG8_MMA(0, 1, At, B1); PG8_BAR; PG8_SCHED;
;             PG8_LDA(At, 0, 1); PG8_STAGE(PG8_SB(0, 0), b2, voffB); PG8_STAGE(PG8_SB(0, 1), b2 + hstepB, voffB); PG8_STAGE(PG8_SA(0, 0), a2, voffA);
;             PG8_WAIT_V(8); PG8_WAIT_L(0); PG8_BAR; PG8_MMA(1, 0, At, B0); PG8_MMA(1, 1, At, B1); PG8_BAR; PG8_SCHED;
.LBB0_200:
	s_add_u32 s4, s48, 0x100
	s_addc_u32 s5, s49, 0
	s_add_u32 s15, s54, 0x100
	s_addc_u32 s42, s55, 0
	s_mov_b32 s43, 0
	s_add_i32 s44, s43, 2
	s_cmp_eq_u32 s68, s43
	s_cselect_b32 s56, s0, s15
	s_cselect_b32 s57, s1, s42
	s_cselect_b32 s54, s94, s4
	s_cselect_b32 s55, s95, s5
	s_add_u32 s48, s56, 0x80
	s_addc_u32 s49, s57, 0
	s_add_u32 s43, s15, s38
	s_addc_u32 s45, s42, 0
	s_add_u32 s58, s43, 0xffffff80
	s_addc_u32 s59, s45, -1
	s_mov_b32 m0, s37
	s_nop 0
	global_load_lds_dwordx4 v0, s[58:59]
	s_nop 0
	s_mov_b32 m0, s41
	s_nop 0
	global_load_lds_dwordx4 v206, s[58:59]
	s_waitcnt vmcnt(8)
	s_waitcnt lgkmcnt(0)
	s_barrier
	s_setprio 1
	s_waitcnt lgkmcnt(0)
	v_mfma_f32_16x16x32_bf16 v[126:129], v[130:133], v[162:165], 0
	v_mfma_f32_16x16x32_bf16 v[126:129], v[134:137], v[166:169], v[126:129]
	v_mfma_f32_16x16x32_bf16 v[122:125], v[138:141], v[162:165], 0
	v_mfma_f32_16x16x32_bf16 v[122:125], v[142:145], v[166:169], v[122:125]
	v_mfma_f32_16x16x32_bf16 v[118:121], v[146:149], v[162:165], 0
	v_mfma_f32_16x16x32_bf16 v[118:121], v[150:153], v[166:169], v[118:121]
	v_mfma_f32_16x16x32_bf16 v[114:117], v[154:157], v[162:165], 0
	v_mfma_f32_16x16x32_bf16 v[114:117], v[158:161], v[166:169], v[114:117]
	v_mfma_f32_16x16x32_bf16 v[98:101], v[154:157], v[170:173], 0
	v_mfma_f32_16x16x32_bf16 v[98:101], v[158:161], v[174:177], v[98:101]
	v_mfma_f32_16x16x32_bf16 v[102:105], v[146:149], v[170:173], 0
	v_mfma_f32_16x16x32_bf16 v[102:105], v[150:153], v[174:177], v[102:105]
	v_mfma_f32_16x16x32_bf16 v[106:109], v[138:141], v[170:173], 0
	v_mfma_f32_16x16x32_bf16 v[106:109], v[142:145], v[174:177], v[106:109]
	v_mfma_f32_16x16x32_bf16 v[110:113], v[130:133], v[170:173], 0
	v_mfma_f32_16x16x32_bf16 v[110:113], v[134:137], v[174:177], v[110:113]
	v_mfma_f32_16x16x32_bf16 v[94:97], v[130:133], v[178:181], 0
	v_mfma_f32_16x16x32_bf16 v[94:97], v[134:137], v[182:185], v[94:97]
	v_mfma_f32_16x16x32_bf16 v[90:93], v[138:141], v[178:181], 0
	v_mfma_f32_16x16x32_bf16 v[90:93], v[142:145], v[182:185], v[90:93]
	v_mfma_f32_16x16x32_bf16 v[86:89], v[146:149], v[178:181], 0
	v_mfma_f32_16x16x32_bf16 v[86:89], v[150:153], v[182:185], v[86:89]
	v_mfma_f32_16x16x32_bf16 v[82:85], v[154:157], v[178:181], 0
	v_mfma_f32_16x16x32_bf16 v[82:85], v[158:161], v[182:185], v[82:85]
	v_mfma_f32_16x16x32_bf16 v[66:69], v[154:157], v[186:189], 0
	v_mfma_f32_16x16x32_bf16 v[66:69], v[158:161], v[190:193], v[66:69]
	v_mfma_f32_16x16x32_bf16 v[70:73], v[146:149], v[186:189], 0
	v_mfma_f32_16x16x32_bf16 v[70:73], v[150:153], v[190:193], v[70:73]
	v_mfma_f32_16x16x32_bf16 v[74:77], v[138:141], v[186:189], 0
	v_mfma_f32_16x16x32_bf16 v[74:77], v[142:145], v[190:193], v[74:77]
	v_mfma_f32_16x16x32_bf16 v[78:81], v[130:133], v[186:189], 0
	v_mfma_f32_16x16x32_bf16 v[78:81], v[134:137], v[190:193], v[78:81]
	s_setprio 0
	s_barrier
	ds_read_b128 v[162:165], v246 offset:16384
	ds_read_b128 v[166:169], v246 offset:17408
	ds_read_b128 v[170:173], v246 offset:18432
	ds_read_b128 v[174:177], v246 offset:19456
	ds_read_b128 v[178:181], v246 offset:20480
	ds_read_b128 v[182:185], v246 offset:21504
	ds_read_b128 v[186:189], v246 offset:22528
	ds_read_b128 v[190:193], v246 offset:23552
	s_mov_b32 m0, s46
	s_nop 0
	global_load_lds_dwordx4 v195, s[54:55]
	s_add_u32 s58, s54, s38
	s_mov_b32 m0, s26
	s_nop 0
	global_load_lds_dwordx4 v207, s[54:55]
	s_addc_u32 s59, s55, 0
	s_mov_b32 m0, s27
	s_nop 0
	global_load_lds_dwordx4 v195, s[58:59]
	s_nop 0
	s_mov_b32 m0, s30
	s_nop 0
	global_load_lds_dwordx4 v207, s[58:59]
	s_nop 0
	s_mov_b32 m0, s29
	s_nop 0
	global_load_lds_dwordx4 v0, s[56:57]
	s_nop 0
	s_mov_b32 m0, s17
	s_nop 0
	global_load_lds_dwordx4 v206, s[56:57]
	s_waitcnt vmcnt(8)
	s_waitcnt lgkmcnt(0)
	s_barrier
	s_setprio 1
	s_waitcnt lgkmcnt(0)
	v_mfma_f32_16x16x32_bf16 v[62:65], v[130:133], v[162:165], 0
	v_mfma_f32_16x16x32_bf16 v[62:65], v[134:137], v[166:169], v[62:65]
	v_mfma_f32_16x16x32_bf16 v[58:61], v[138:141], v[162:165], 0
	v_mfma_f32_16x16x32_bf16 v[58:61], v[142:145], v[166:169], v[58:61]
	v_mfma_f32_16x16x32_bf16 v[54:57], v[146:149], v[162:165], 0
	v_mfma_f32_16x16x32_bf16 v[54:57], v[150:153], v[166:169], v[54:57]
	v_mfma_f32_16x16x32_bf16 v[50:53], v[154:157], v[162:165], 0
	v_mfma_f32_16x16x32_bf16 v[50:53], v[158:161], v[166:169], v[50:53]
	v_mfma_f32_16x16x32_bf16 v[34:37], v[154:157], v[170:173], 0
	v_mfma_f32_16x16x32_bf16 v[34:37], v[158:161], v[174:177], v[34:37]
	v_mfma_f32_16x16x32_bf16 v[38:41], v[146:149], v[170:173], 0
	v_mfma_f32_16x16x32_bf16 v[38:41], v[150:153], v[174:177], v[38:41]
	v_mfma_f32_16x16x32_bf16 v[42:45], v[138:141], v[170:173], 0
	v_mfma_f32_16x16x32_bf16 v[42:45], v[142:145], v[174:177], v[42:45]
	v_mfma_f32_16x16x32_bf16 v[46:49], v[130:133], v[170:173], 0
	v_mfma_f32_16x16x32_bf16 v[46:49], v[134:137], v[174:177], v[46:49]
	v_mfma_f32_16x16x32_bf16 v[30:33], v[130:133], v[178:181], 0
	v_mfma_f32_16x16x32_bf16 v[30:33], v[134:137], v[182:185], v[30:33]
	v_mfma_f32_16x16x32_bf16 v[26:29], v[138:141], v[178:181], 0
	v_mfma_f32_16x16x32_bf16 v[26:29], v[142:145], v[182:185], v[26:29]
	v_mfma_f32_16x16x32_bf16 v[22:25], v[146:149], v[178:181], 0
	v_mfma_f32_16x16x32_bf16 v[22:25], v[150:153], v[182:185], v[22:25]
	v_mfma_f32_16x16x32_bf16 v[18:21], v[154:157], v[178:181], 0
	v_mfma_f32_16x16x32_bf16 v[18:21], v[158:161], v[182:185], v[18:21]
	v_mfma_f32_16x16x32_bf16 v[2:5], v[154:157], v[186:189], 0
	v_mfma_f32_16x16x32_bf16 v[2:5], v[158:161], v[190:193], v[2:5]
	v_mfma_f32_16x16x32_bf16 v[6:9], v[146:149], v[186:189], 0
	v_mfma_f32_16x16x32_bf16 v[6:9], v[150:153], v[190:193], v[6:9]
	v_mfma_f32_16x16x32_bf16 v[10:13], v[138:141], v[186:189], 0
	v_mfma_f32_16x16x32_bf16 v[10:13], v[142:145], v[190:193], v[10:13]
	v_mfma_f32_16x16x32_bf16 v[14:17], v[130:133], v[186:189], 0
	v_mfma_f32_16x16x32_bf16 v[14:17], v[134:137], v[190:193], v[14:17]
	s_setprio 0
	s_barrier
; #define PG8_STAGE(bufoff, gbase, voff) do { _Pragma("unroll") for (int _i = 0; _i < 2; ++_i) { \
;         const unsigned _m0 = ldsb + (unsigned)((bufoff) + _i * 8192); const char* _gb = (const char*)(gbase); \
;         asm volatile("s_mov_b32 m0, %0\n\ts_nop 0\n\tglobal_load_lds_dwordx4 %1, %2" :: "s"(_m0), "v"((voff)[_i]), "s"(_gb) : "m0", "memory"); } } while (0)
; #define PG8_LDA(dst, b, h) do { _Pragma("unroll") for (int m = 0; m < 4; ++m) _Pragma("unroll") for (int k = 0; k < 2; ++k) dst[m][k] = *(const LAS bf16x8*)(lds + PG8_SA(b, h) + aoff + m * 2048 + k * 1024); } while (0)
; #define PG8_LDB(dst, b, h) do { _Pragma("unroll") for (int n = 0; n < 2; ++n) _Pragma("unroll") for (int k = 0; k < 2; ++k) dst[n][k] = *(const LAS bf16x8*)(lds + PG8_SB(b, h) + boff + n * 2048 + k * 1024); } while (0)
; #define PG8_MMA(ai, bj, At, Bt) do { __builtin_amdgcn_s_setprio(1); _Pragma("unroll") for (int m = 0; m < 4; ++m) _Pragma("unroll") for (int n = 0; n < 2; ++n) _Pragma("unroll") for (int k = 0; k < 2; ++k) \
;         acc[ai][bj][m][n] = __builtin_amdgcn_mfma_f32_16x16x32_bf16(Bt[n][k], At[m][k], acc[ai][bj][m][n], 0, 0, 0); __builtin_amdgcn_s_setprio(0); } while (0)
; #define PG8_WAIT_V(n) asm volatile("s_waitcnt vmcnt(" #n ")" ::: "memory")
; #define PG8_WAIT_L(n) asm volatile("s_waitcnt lgkmcnt(" #n ")" ::: "memory")
; #define PG8_BAR __builtin_amdgcn_s_barrier()
; #define PG8_SCHED __builtin_amdgcn_sched_barrier(0)
; template <class Epi, bool ALIGN_EPI>
; __device__ __forceinline__ void gemm_phase(LAS unsigned char* lds, const Gemm g, const StaticOrder& S, const Epi& E) {
;     ...
;             PG8_LDB(B0, 1, 0); PG8_LDB(B1, 1, 1); PG8_SCHED; PG8_LDA(At, 1, 0); PG8_STAGE(PG8_SA(0, 1), a2 + hstepA, voffA);
;             PG8_WAIT_V(8); PG8_WAIT_L(0); PG8_BAR; PG8_MMA(0, 0, At, B0); PG8_MMA(0, 1, At, B1); PG8_BAR; PG8_SCHED;
;             PG8_LDA(At, 1, 1); PG8_STAGE(PG8_SB(1, 0), b3, voffB); PG8_STAGE(PG8_SB(1, 1), b3 + hstepB, voffB); PG8_STAGE(PG8_SA(1, 0), a3, voffA);
;             PG8_WAIT_V(8); PG8_WAIT_L(0); PG8_BAR; PG8_MMA(1, 0, At, B0); PG8_MMA(1, 1, At, B1); PG8_BAR; PG8_SCHED;
;         }
	v_add_u32_e32 v142, 0x18000, v245
	v_add_u32_e32 v158, 0x1c000, v245
	ds_read_b128 v[130:133], v142
	ds_read_b128 v[134:137], v142 offset:1024
	ds_read_b128 v[138:141], v142 offset:2048
	ds_read_b128 v[142:145], v142 offset:3072
	ds_read_b128 v[146:149], v158
	ds_read_b128 v[150:153], v158 offset:1024
	ds_read_b128 v[154:157], v158 offset:2048
	ds_read_b128 v[158:161], v158 offset:3072
	ds_read_b128 v[162:165], v246 offset:32768
	ds_read_b128 v[166:169], v246 offset:33792
	ds_read_b128 v[170:173], v246 offset:34816
	ds_read_b128 v[174:177], v246 offset:35840
	ds_read_b128 v[178:181], v246 offset:36864
	ds_read_b128 v[182:185], v246 offset:37888
	ds_read_b128 v[186:189], v246 offset:38912
	ds_read_b128 v[190:193], v246 offset:39936
	s_add_u32 s56, s56, s38
	s_addc_u32 s57, s57, 0
	s_mov_b32 m0, s31
	s_nop 0
	global_load_lds_dwordx4 v0, s[56:57]
	s_nop 0
	s_mov_b32 m0, s53
	s_nop 0
	global_load_lds_dwordx4 v206, s[56:57]
	s_waitcnt vmcnt(8)
	s_waitcnt lgkmcnt(0)
	s_barrier
	s_setprio 1
	s_waitcnt lgkmcnt(0)
	v_mfma_f32_16x16x32_bf16 v[126:129], v[130:133], v[162:165], v[126:129]
	v_mfma_f32_16x16x32_bf16 v[126:129], v[134:137], v[166:169], v[126:129]
	v_mfma_f32_16x16x32_bf16 v[122:125], v[138:141], v[162:165], v[122:125]
	v_mfma_f32_16x16x32_bf16 v[122:125], v[142:145], v[166:169], v[122:125]
	v_mfma_f32_16x16x32_bf16 v[118:121], v[146:149], v[162:165], v[118:121]
	v_mfma_f32_16x16x32_bf16 v[118:121], v[150:153], v[166:169], v[118:121]
	v_mfma_f32_16x16x32_bf16 v[114:117], v[154:157], v[162:165], v[114:117]
	v_mfma_f32_16x16x32_bf16 v[114:117], v[158:161], v[166:169], v[114:117]
	v_mfma_f32_16x16x32_bf16 v[98:101], v[154:157], v[170:173], v[98:101]
	v_mfma_f32_16x16x32_bf16 v[98:101], v[158:161], v[174:177], v[98:101]
	v_mfma_f32_16x16x32_bf16 v[102:105], v[146:149], v[170:173], v[102:105]
	v_mfma_f32_16x16x32_bf16 v[102:105], v[150:153], v[174:177], v[102:105]
	v_mfma_f32_16x16x32_bf16 v[106:109], v[138:141], v[170:173], v[106:109]
	v_mfma_f32_16x16x32_bf16 v[106:109], v[142:145], v[174:177], v[106:109]
	v_mfma_f32_16x16x32_bf16 v[110:113], v[130:133], v[170:173], v[110:113]
	v_mfma_f32_16x16x32_bf16 v[110:113], v[134:137], v[174:177], v[110:113]
	v_mfma_f32_16x16x32_bf16 v[94:97], v[130:133], v[178:181], v[94:97]
	v_mfma_f32_16x16x32_bf16 v[94:97], v[134:137], v[182:185], v[94:97]
	v_mfma_f32_16x16x32_bf16 v[90:93], v[138:141], v[178:181], v[90:93]
	v_mfma_f32_16x16x32_bf16 v[90:93], v[142:145], v[182:185], v[90:93]
	v_mfma_f32_16x16x32_bf16 v[86:89], v[146:149], v[178:181], v[86:89]
	v_mfma_f32_16x16x32_bf16 v[86:89], v[150:153], v[182:185], v[86:89]
	v_mfma_f32_16x16x32_bf16 v[82:85], v[154:157], v[178:181], v[82:85]
	v_mfma_f32_16x16x32_bf16 v[82:85], v[158:161], v[182:185], v[82:85]
	v_mfma_f32_16x16x32_bf16 v[66:69], v[154:157], v[186:189], v[66:69]
	v_mfma_f32_16x16x32_bf16 v[66:69], v[158:161], v[190:193], v[66:69]
	v_mfma_f32_16x16x32_bf16 v[70:73], v[146:149], v[186:189], v[70:73]
	v_mfma_f32_16x16x32_bf16 v[70:73], v[150:153], v[190:193], v[70:73]
	v_mfma_f32_16x16x32_bf16 v[74:77], v[138:141], v[186:189], v[74:77]
	v_mfma_f32_16x16x32_bf16 v[74:77], v[142:145], v[190:193], v[74:77]
	v_mfma_f32_16x16x32_bf16 v[78:81], v[130:133], v[186:189], v[78:81]
	v_mfma_f32_16x16x32_bf16 v[78:81], v[134:137], v[190:193], v[78:81]
	s_setprio 0
	s_barrier
	ds_read_b128 v[162:165], v246 offset:49152
	ds_read_b128 v[166:169], v246 offset:50176
	ds_read_b128 v[170:173], v246 offset:51200
	ds_read_b128 v[174:177], v246 offset:52224
	ds_read_b128 v[178:181], v246 offset:53248
	ds_read_b128 v[182:185], v246 offset:54272
	ds_read_b128 v[186:189], v246 offset:55296
	ds_read_b128 v[190:193], v246 offset:56320
	s_add_u32 s54, s54, 0x80
	s_addc_u32 s55, s55, 0
	s_mov_b32 m0, s85
	s_nop 0
	global_load_lds_dwordx4 v195, s[54:55]
	s_nop 0
	s_mov_b32 m0, s65
	s_nop 0
	global_load_lds_dwordx4 v207, s[54:55]
	s_add_u32 s54, s58, 0x80
	s_addc_u32 s55, s59, 0
	s_mov_b32 m0, s93
	s_nop 0
	global_load_lds_dwordx4 v195, s[54:55]
	s_nop 0
	s_mov_b32 m0, s28
	s_nop 0
	global_load_lds_dwordx4 v207, s[54:55]
	s_nop 0
	s_mov_b32 m0, s67
	s_nop 0
	global_load_lds_dwordx4 v0, s[48:49]
	s_nop 0
	s_mov_b32 m0, s92
	s_nop 0
	global_load_lds_dwordx4 v206, s[48:49]
	s_waitcnt vmcnt(8)
	s_waitcnt lgkmcnt(0)
	s_barrier
	s_setprio 1
	s_waitcnt lgkmcnt(0)
	v_mfma_f32_16x16x32_bf16 v[62:65], v[130:133], v[162:165], v[62:65]
	v_mfma_f32_16x16x32_bf16 v[62:65], v[134:137], v[166:169], v[62:65]
	v_mfma_f32_16x16x32_bf16 v[58:61], v[138:141], v[162:165], v[58:61]
	v_mfma_f32_16x16x32_bf16 v[58:61], v[142:145], v[166:169], v[58:61]
	v_mfma_f32_16x16x32_bf16 v[54:57], v[146:149], v[162:165], v[54:57]
	v_mfma_f32_16x16x32_bf16 v[54:57], v[150:153], v[166:169], v[54:57]
	v_mfma_f32_16x16x32_bf16 v[50:53], v[154:157], v[162:165], v[50:53]
	v_mfma_f32_16x16x32_bf16 v[50:53], v[158:161], v[166:169], v[50:53]
	v_mfma_f32_16x16x32_bf16 v[34:37], v[154:157], v[170:173], v[34:37]
	v_mfma_f32_16x16x32_bf16 v[34:37], v[158:161], v[174:177], v[34:37]
	v_mfma_f32_16x16x32_bf16 v[38:41], v[146:149], v[170:173], v[38:41]
	v_mfma_f32_16x16x32_bf16 v[38:41], v[150:153], v[174:177], v[38:41]
	v_mfma_f32_16x16x32_bf16 v[42:45], v[138:141], v[170:173], v[42:45]
	v_mfma_f32_16x16x32_bf16 v[42:45], v[142:145], v[174:177], v[42:45]
	v_mfma_f32_16x16x32_bf16 v[46:49], v[130:133], v[170:173], v[46:49]
	v_mfma_f32_16x16x32_bf16 v[46:49], v[134:137], v[174:177], v[46:49]
	v_mfma_f32_16x16x32_bf16 v[30:33], v[130:133], v[178:181], v[30:33]
	v_mfma_f32_16x16x32_bf16 v[30:33], v[134:137], v[182:185], v[30:33]
	v_mfma_f32_16x16x32_bf16 v[26:29], v[138:141], v[178:181], v[26:29]
	v_mfma_f32_16x16x32_bf16 v[26:29], v[142:145], v[182:185], v[26:29]
	v_mfma_f32_16x16x32_bf16 v[22:25], v[146:149], v[178:181], v[22:25]
	v_mfma_f32_16x16x32_bf16 v[22:25], v[150:153], v[182:185], v[22:25]
	v_mfma_f32_16x16x32_bf16 v[18:21], v[154:157], v[178:181], v[18:21]
	v_mfma_f32_16x16x32_bf16 v[18:21], v[158:161], v[182:185], v[18:21]
	v_mfma_f32_16x16x32_bf16 v[2:5], v[154:157], v[186:189], v[2:5]
	v_mfma_f32_16x16x32_bf16 v[2:5], v[158:161], v[190:193], v[2:5]
	v_mfma_f32_16x16x32_bf16 v[6:9], v[146:149], v[186:189], v[6:9]
	v_mfma_f32_16x16x32_bf16 v[6:9], v[150:153], v[190:193], v[6:9]
	v_mfma_f32_16x16x32_bf16 v[10:13], v[138:141], v[186:189], v[10:13]
	v_mfma_f32_16x16x32_bf16 v[10:13], v[142:145], v[190:193], v[10:13]
	v_mfma_f32_16x16x32_bf16 v[14:17], v[130:133], v[186:189], v[14:17]
	v_mfma_f32_16x16x32_bf16 v[14:17], v[134:137], v[190:193], v[14:17]
	s_setprio 0
	s_barrier
	s_add_u32 s4, s4, 0x100
	s_addc_u32 s5, s5, 0
	s_add_u32 s15, s15, 0x100
	s_addc_u32 s42, s42, 0
	s_cmp_ge_u32 s44, s36
	s_mov_b32 s43, s44

; #define PG8_STAGE(bufoff, gbase, voff) do { _Pragma("unroll") for (int _i = 0; _i < 2; ++_i) { \
;         const unsigned _m0 = ldsb + (unsigned)((bufoff) + _i * 8192); const char* _gb = (const char*)(gbase); \
;         asm volatile("s_mov_b32 m0, %0\n\ts_nop 0\n\tglobal_load_lds_dwordx4 %1, %2" :: "s"(_m0), "v"((voff)[_i]), "s"(_gb) : "m0", "memory"); } } while (0)
; #define PG8_LDA(dst, b, h) do { _Pragma("unroll") for (int m = 0; m < 4; ++m) _Pragma("unroll") for (int k = 0; k < 2; ++k) dst[m][k] = *(const LAS bf16x8*)(lds + PG8_SA(b, h) + aoff + m * 2048 + k * 1024); } while (0)
; #define PG8_LDB(dst, b, h) do { _Pragma("unroll") for (int n = 0; n < 2; ++n) _Pragma("unroll") for (int k = 0; k < 2; ++k) dst[n][k] = *(const LAS bf16x8*)(lds + PG8_SB(b, h) + boff + n * 2048 + k * 1024); } while (0)
; #define PG8_SCHED __builtin_amdgcn_sched_barrier(0)
;     __device__ bool next(int i, Unit& u) const {
;         const long L = (long)i * G + c; if (L >= nwg) return false;
;         int wgid = (int)L; { const int q = nwg / NXCD, r = nwg % NXCD, xcd = wgid % NXCD, off = wgid / NXCD; wgid = (xcd < r ? xcd * (q + 1) : r * (q + 1) + (xcd - r) * q) + off; }
; template <class Epi, bool ALIGN_EPI>
; __device__ __forceinline__ void gemm_phase(LAS unsigned char* lds, const Gemm g, const StaticOrder& S, const Epi& E) {
;     ...
;             PG8_LDB(B0, 0, 0); PG8_LDB(B1, 0, 1); PG8_SCHED; PG8_LDA(At, 0, 0); PG8_STAGE(PG8_SA(1, 1), a1 + hstepA, voffA);
.LBB0_260:
	v_add_u32_e32 v0, 0x10000, v179
	ds_read_b128 v[130:133], v0
	ds_read_b128 v[134:137], v0 offset:1024
	ds_read_b128 v[138:141], v0 offset:2048
	ds_read_b128 v[142:145], v0 offset:3072
	v_add_u32_e32 v0, 0x14000, v179
	ds_read_b128 v[146:149], v0
	ds_read_b128 v[150:153], v0 offset:1024
	ds_read_b128 v[154:157], v0 offset:2048
	ds_read_b128 v[158:161], v0 offset:3072
	ds_read_b128 v[182:185], v180
	ds_read_b128 v[186:189], v180 offset:1024
	ds_read_b128 v[190:193], v180 offset:2048
	ds_read_b128 v[202:205], v180 offset:3072
	ds_read_b128 v[206:209], v180 offset:4096
	ds_read_b128 v[210:213], v180 offset:5120
	ds_read_b128 v[214:217], v180 offset:6144
	ds_read_b128 v[240:243], v180 offset:7168
	s_add_i32 s85, s85, 1
	s_mul_i32 s0, s85, s80
	s_mul_hi_u32 s1, s85, s87
	s_add_i32 s1, s1, s0
	s_mul_i32 s0, s85, s87
	s_add_u32 s4, s0, s16
	s_addc_u32 s5, s1, s38
	v_cmp_gt_i64_e32 vcc, s[4:5], v[198:199]
	v_cmp_lt_i64_e64 s[0:1], s[4:5], v[196:197]
	s_cbranch_vccnz .LBB0_266
	s_ashr_i32 s5, s4, 31
	s_lshr_b32 s5, s5, 29
	s_add_i32 s6, s4, s5
	s_and_b32 s5, s6, -8
	s_sub_i32 s7, s4, s5
	s_cmp_gt_i32 s7, -1
	s_mov_b64 s[4:5], -1
	s_cbranch_scc0 .LBB0_263
	s_lshl_b32 s39, s7, 6
	s_mov_b64 s[4:5], 0

; #define PG8_STAGE(bufoff, gbase, voff) do { _Pragma("unroll") for (int _i = 0; _i < 2; ++_i) { \
;         const unsigned _m0 = ldsb + (unsigned)((bufoff) + _i * 8192); const char* _gb = (const char*)(gbase); \
;         asm volatile("s_mov_b32 m0, %0\n\ts_nop 0\n\tglobal_load_lds_dwordx4 %1, %2" :: "s"(_m0), "v"((voff)[_i]), "s"(_gb) : "m0", "memory"); } } while (0)
; #define PG8_LDA(dst, b, h) do { _Pragma("unroll") for (int m = 0; m < 4; ++m) _Pragma("unroll") for (int k = 0; k < 2; ++k) dst[m][k] = *(const LAS bf16x8*)(lds + PG8_SA(b, h) + aoff + m * 2048 + k * 1024); } while (0)
; #define PG8_LDB(dst, b, h) do { _Pragma("unroll") for (int n = 0; n < 2; ++n) _Pragma("unroll") for (int k = 0; k < 2; ++k) dst[n][k] = *(const LAS bf16x8*)(lds + PG8_SB(b, h) + boff + n * 2048 + k * 1024); } while (0)
; #define PG8_MMA(ai, bj, At, Bt) do { __builtin_amdgcn_s_setprio(1); _Pragma("unroll") for (int m = 0; m < 4; ++m) _Pragma("unroll") for (int n = 0; n < 2; ++n) _Pragma("unroll") for (int k = 0; k < 2; ++k) \
;         acc[ai][bj][m][n] = __builtin_amdgcn_mfma_f32_16x16x32_bf16(Bt[n][k], At[m][k], acc[ai][bj][m][n], 0, 0, 0); __builtin_amdgcn_s_setprio(0); } while (0)
; #define PG8_WAIT_V(n) asm volatile("s_waitcnt vmcnt(" #n ")" ::: "memory")
; #define PG8_WAIT_L(n) asm volatile("s_waitcnt lgkmcnt(" #n ")" ::: "memory")
; #define PG8_BAR __builtin_amdgcn_s_barrier()
; #define PG8_SCHED __builtin_amdgcn_sched_barrier(0)
; template <class Epi, bool ALIGN_EPI>
; __device__ __forceinline__ void gemm_phase(LAS unsigned char* lds, const Gemm g, const StaticOrder& S, const Epi& E) {
;     ...
;             const char* a1 = cA + (size_t)(t + 1) * kstep;
;             const char* a2 = last ? nA : cA + (size_t)(t + 2) * kstep; const char* b2 = last ? nB : cB + (size_t)(t + 2) * kstep;
;             const char* a3 = a2 + kstep; const char* b3 = b2 + kstep;
;             PG8_LDB(B0, 0, 0); PG8_LDB(B1, 0, 1); PG8_SCHED; PG8_LDA(At, 0, 0); PG8_STAGE(PG8_SA(1, 1), a1 + hstepA, voffA);
;             PG8_WAIT_V(8); PG8_WAIT_L(0); PG8_BAR; PG8_MMA(0, 0, At, B0); PG8_MMA(0, 1, At, B1); PG8_BAR; PG8_SCHED;
;             PG8_LDA(At, 0, 1); PG8_STAGE(PG8_SB(0, 0), b2, voffB); PG8_STAGE(PG8_SB(0, 1), b2 + hstepB, voffB); PG8_STAGE(PG8_SA(0, 0), a2, voffA);
;             PG8_WAIT_V(8); PG8_WAIT_L(0); PG8_BAR; PG8_MMA(1, 0, At, B0); PG8_MMA(1, 1, At, B1); PG8_BAR; PG8_SCHED;
.LBB0_270:
	s_add_u32 s4, s56, 0x100
	s_addc_u32 s5, s57, 0
	s_add_u32 s0, s58, 0x40080
	s_addc_u32 s1, s59, 0
	s_mov_b32 s44, 0
	s_add_i32 s55, s44, 2
	s_add_u32 s45, s0, 0xfffc0080
	s_addc_u32 s56, s1, -1
	s_cmp_eq_u32 s68, s44
	s_cselect_b32 s60, s96, s45
	s_cselect_b32 s61, s97, s56
	s_cselect_b32 s58, s48, s4
	s_cselect_b32 s59, s49, s5
	s_add_u32 s56, s60, 0x80
	s_addc_u32 s57, s61, 0
	s_mov_b32 m0, s41
	s_nop 0
	global_load_lds_dwordx4 v165, s[0:1]
	s_nop 0
	s_mov_b32 m0, s30
	s_nop 0
	global_load_lds_dwordx4 v171, s[0:1]
	s_waitcnt vmcnt(8)
	s_waitcnt lgkmcnt(0)
	s_barrier
	s_setprio 1
	s_waitcnt lgkmcnt(0)
	v_mfma_f32_16x16x32_bf16 v[126:129], v[130:133], v[182:185], 0
	v_mfma_f32_16x16x32_bf16 v[126:129], v[134:137], v[186:189], v[126:129]
	v_mfma_f32_16x16x32_bf16 v[122:125], v[138:141], v[182:185], 0
	v_mfma_f32_16x16x32_bf16 v[122:125], v[142:145], v[186:189], v[122:125]
	v_mfma_f32_16x16x32_bf16 v[118:121], v[146:149], v[182:185], 0
	v_mfma_f32_16x16x32_bf16 v[118:121], v[150:153], v[186:189], v[118:121]
	v_mfma_f32_16x16x32_bf16 v[110:113], v[154:157], v[182:185], 0
	v_mfma_f32_16x16x32_bf16 v[110:113], v[158:161], v[186:189], v[110:113]
	v_mfma_f32_16x16x32_bf16 v[94:97], v[154:157], v[190:193], 0
	v_mfma_f32_16x16x32_bf16 v[94:97], v[158:161], v[202:205], v[94:97]
	v_mfma_f32_16x16x32_bf16 v[102:105], v[146:149], v[190:193], 0
	v_mfma_f32_16x16x32_bf16 v[102:105], v[150:153], v[202:205], v[102:105]
	v_mfma_f32_16x16x32_bf16 v[106:109], v[138:141], v[190:193], 0
	v_mfma_f32_16x16x32_bf16 v[106:109], v[142:145], v[202:205], v[106:109]
	v_mfma_f32_16x16x32_bf16 v[114:117], v[130:133], v[190:193], 0
	v_mfma_f32_16x16x32_bf16 v[114:117], v[134:137], v[202:205], v[114:117]
	v_mfma_f32_16x16x32_bf16 v[98:101], v[130:133], v[206:209], 0
	v_mfma_f32_16x16x32_bf16 v[98:101], v[134:137], v[210:213], v[98:101]
	v_mfma_f32_16x16x32_bf16 v[90:93], v[138:141], v[206:209], 0
	v_mfma_f32_16x16x32_bf16 v[90:93], v[142:145], v[210:213], v[90:93]
	v_mfma_f32_16x16x32_bf16 v[86:89], v[146:149], v[206:209], 0
	v_mfma_f32_16x16x32_bf16 v[86:89], v[150:153], v[210:213], v[86:89]
	v_mfma_f32_16x16x32_bf16 v[78:81], v[154:157], v[206:209], 0
	v_mfma_f32_16x16x32_bf16 v[78:81], v[158:161], v[210:213], v[78:81]
	v_mfma_f32_16x16x32_bf16 v[66:69], v[154:157], v[214:217], 0
	v_mfma_f32_16x16x32_bf16 v[66:69], v[158:161], v[240:243], v[66:69]
	v_mfma_f32_16x16x32_bf16 v[70:73], v[146:149], v[214:217], 0
	v_mfma_f32_16x16x32_bf16 v[70:73], v[150:153], v[240:243], v[70:73]
	v_mfma_f32_16x16x32_bf16 v[74:77], v[138:141], v[214:217], 0
	v_mfma_f32_16x16x32_bf16 v[74:77], v[142:145], v[240:243], v[74:77]
	v_mfma_f32_16x16x32_bf16 v[82:85], v[130:133], v[214:217], 0
	v_mfma_f32_16x16x32_bf16 v[82:85], v[134:137], v[240:243], v[82:85]
	s_setprio 0
	s_barrier
	ds_read_b128 v[182:185], v180 offset:16384
	ds_read_b128 v[186:189], v180 offset:17408
	ds_read_b128 v[190:193], v180 offset:18432
	ds_read_b128 v[202:205], v180 offset:19456
	ds_read_b128 v[206:209], v180 offset:20480
	ds_read_b128 v[210:213], v180 offset:21504
	ds_read_b128 v[214:217], v180 offset:22528
	ds_read_b128 v[240:243], v180 offset:23552
	s_mov_b32 m0, s42
	s_nop 0
	global_load_lds_dwordx4 v167, s[58:59]
	s_add_u32 s44, s58, s14
	s_mov_b32 m0, s43
	s_nop 0
	global_load_lds_dwordx4 v175, s[58:59]
	s_addc_u32 s45, s59, 0
	s_mov_b32 m0, s46
	s_nop 0
	global_load_lds_dwordx4 v167, s[44:45]
	s_nop 0
	s_mov_b32 m0, s50
	s_nop 0
	global_load_lds_dwordx4 v175, s[44:45]
	s_nop 0
	s_mov_b32 m0, s17
	s_nop 0
	global_load_lds_dwordx4 v165, s[60:61]
	s_nop 0
	s_mov_b32 m0, s53
	s_nop 0
	global_load_lds_dwordx4 v171, s[60:61]
	s_waitcnt vmcnt(8)
	s_waitcnt lgkmcnt(0)
	s_barrier
	s_setprio 1
	s_waitcnt lgkmcnt(0)
	v_mfma_f32_16x16x32_bf16 v[62:65], v[130:133], v[182:185], 0
	v_mfma_f32_16x16x32_bf16 v[62:65], v[134:137], v[186:189], v[62:65]
	v_mfma_f32_16x16x32_bf16 v[58:61], v[138:141], v[182:185], 0
	v_mfma_f32_16x16x32_bf16 v[58:61], v[142:145], v[186:189], v[58:61]
	v_mfma_f32_16x16x32_bf16 v[54:57], v[146:149], v[182:185], 0
	v_mfma_f32_16x16x32_bf16 v[54:57], v[150:153], v[186:189], v[54:57]
	v_mfma_f32_16x16x32_bf16 v[50:53], v[154:157], v[182:185], 0
	v_mfma_f32_16x16x32_bf16 v[50:53], v[158:161], v[186:189], v[50:53]
	v_mfma_f32_16x16x32_bf16 v[30:33], v[154:157], v[190:193], 0
	v_mfma_f32_16x16x32_bf16 v[30:33], v[158:161], v[202:205], v[30:33]
	v_mfma_f32_16x16x32_bf16 v[38:41], v[146:149], v[190:193], 0
	v_mfma_f32_16x16x32_bf16 v[38:41], v[150:153], v[202:205], v[38:41]
	v_mfma_f32_16x16x32_bf16 v[42:45], v[138:141], v[190:193], 0
	v_mfma_f32_16x16x32_bf16 v[42:45], v[142:145], v[202:205], v[42:45]
	v_mfma_f32_16x16x32_bf16 v[46:49], v[130:133], v[190:193], 0
	v_mfma_f32_16x16x32_bf16 v[46:49], v[134:137], v[202:205], v[46:49]
	v_mfma_f32_16x16x32_bf16 v[34:37], v[130:133], v[206:209], 0
	v_mfma_f32_16x16x32_bf16 v[34:37], v[134:137], v[210:213], v[34:37]
	v_mfma_f32_16x16x32_bf16 v[26:29], v[138:141], v[206:209], 0
	v_mfma_f32_16x16x32_bf16 v[26:29], v[142:145], v[210:213], v[26:29]
	v_mfma_f32_16x16x32_bf16 v[22:25], v[146:149], v[206:209], 0
	v_mfma_f32_16x16x32_bf16 v[22:25], v[150:153], v[210:213], v[22:25]
	v_mfma_f32_16x16x32_bf16 v[14:17], v[154:157], v[206:209], 0
	v_mfma_f32_16x16x32_bf16 v[14:17], v[158:161], v[210:213], v[14:17]
	v_mfma_f32_16x16x32_bf16 v[2:5], v[154:157], v[214:217], 0
	v_mfma_f32_16x16x32_bf16 v[2:5], v[158:161], v[240:243], v[2:5]
	v_mfma_f32_16x16x32_bf16 v[6:9], v[146:149], v[214:217], 0
	v_mfma_f32_16x16x32_bf16 v[6:9], v[150:153], v[240:243], v[6:9]
	v_mfma_f32_16x16x32_bf16 v[10:13], v[138:141], v[214:217], 0
	v_mfma_f32_16x16x32_bf16 v[10:13], v[142:145], v[240:243], v[10:13]
	v_mfma_f32_16x16x32_bf16 v[18:21], v[130:133], v[214:217], 0
	v_mfma_f32_16x16x32_bf16 v[18:21], v[134:137], v[240:243], v[18:21]
	s_setprio 0
	s_barrier
; #define PG8_STAGE(bufoff, gbase, voff) do { _Pragma("unroll") for (int _i = 0; _i < 2; ++_i) { \
;         const unsigned _m0 = ldsb + (unsigned)((bufoff) + _i * 8192); const char* _gb = (const char*)(gbase); \
;         asm volatile("s_mov_b32 m0, %0\n\ts_nop 0\n\tglobal_load_lds_dwordx4 %1, %2" :: "s"(_m0), "v"((voff)[_i]), "s"(_gb) : "m0", "memory"); } } while (0)
; #define PG8_LDA(dst, b, h) do { _Pragma("unroll") for (int m = 0; m < 4; ++m) _Pragma("unroll") for (int k = 0; k < 2; ++k) dst[m][k] = *(const LAS bf16x8*)(lds + PG8_SA(b, h) + aoff + m * 2048 + k * 1024); } while (0)
; #define PG8_LDB(dst, b, h) do { _Pragma("unroll") for (int n = 0; n < 2; ++n) _Pragma("unroll") for (int k = 0; k < 2; ++k) dst[n][k] = *(const LAS bf16x8*)(lds + PG8_SB(b, h) + boff + n * 2048 + k * 1024); } while (0)
; #define PG8_MMA(ai, bj, At, Bt) do { __builtin_amdgcn_s_setprio(1); _Pragma("unroll") for (int m = 0; m < 4; ++m) _Pragma("unroll") for (int n = 0; n < 2; ++n) _Pragma("unroll") for (int k = 0; k < 2; ++k) \
;         acc[ai][bj][m][n] = __builtin_amdgcn_mfma_f32_16x16x32_bf16(Bt[n][k], At[m][k], acc[ai][bj][m][n], 0, 0, 0); __builtin_amdgcn_s_setprio(0); } while (0)
; #define PG8_WAIT_V(n) asm volatile("s_waitcnt vmcnt(" #n ")" ::: "memory")
; #define PG8_WAIT_L(n) asm volatile("s_waitcnt lgkmcnt(" #n ")" ::: "memory")
; #define PG8_BAR __builtin_amdgcn_s_barrier()
; #define PG8_SCHED __builtin_amdgcn_sched_barrier(0)
; template <class Epi, bool ALIGN_EPI>
; __device__ __forceinline__ void gemm_phase(LAS unsigned char* lds, const Gemm g, const StaticOrder& S, const Epi& E) {
;     ...
;             PG8_LDB(B0, 1, 0); PG8_LDB(B1, 1, 1); PG8_SCHED; PG8_LDA(At, 1, 0); PG8_STAGE(PG8_SA(0, 1), a2 + hstepA, voffA);
;             PG8_WAIT_V(8); PG8_WAIT_L(0); PG8_BAR; PG8_MMA(0, 0, At, B0); PG8_MMA(0, 1, At, B1); PG8_BAR; PG8_SCHED;
;             PG8_LDA(At, 1, 1); PG8_STAGE(PG8_SB(1, 0), b3, voffB); PG8_STAGE(PG8_SB(1, 1), b3 + hstepB, voffB); PG8_STAGE(PG8_SA(1, 0), a3, voffA);
;             PG8_WAIT_V(8); PG8_WAIT_L(0); PG8_BAR; PG8_MMA(1, 0, At, B0); PG8_MMA(1, 1, At, B1); PG8_BAR; PG8_SCHED;
;         }
	v_add_u32_e32 v0, 0x18000, v179
	ds_read_b128 v[130:133], v0
	ds_read_b128 v[134:137], v0 offset:1024
	ds_read_b128 v[138:141], v0 offset:2048
	ds_read_b128 v[142:145], v0 offset:3072
	v_add_u32_e32 v0, 0x1c000, v179
	ds_read_b128 v[146:149], v0
	ds_read_b128 v[150:153], v0 offset:1024
	ds_read_b128 v[154:157], v0 offset:2048
	ds_read_b128 v[158:161], v0 offset:3072
	ds_read_b128 v[182:185], v180 offset:32768
	ds_read_b128 v[186:189], v180 offset:33792
	ds_read_b128 v[190:193], v180 offset:34816
	ds_read_b128 v[202:205], v180 offset:35840
	ds_read_b128 v[206:209], v180 offset:36864
	ds_read_b128 v[210:213], v180 offset:37888
	ds_read_b128 v[214:217], v180 offset:38912
	ds_read_b128 v[240:243], v180 offset:39936
	s_add_u32 s60, s60, 0x40000
	s_addc_u32 s61, s61, 0
	s_mov_b32 m0, s65
	s_nop 0
	global_load_lds_dwordx4 v165, s[60:61]
	s_nop 0
	s_mov_b32 m0, s67
	s_nop 0
	global_load_lds_dwordx4 v171, s[60:61]
	s_waitcnt vmcnt(8)
	s_waitcnt lgkmcnt(0)
	s_barrier
	s_setprio 1
	s_waitcnt lgkmcnt(0)
	v_mfma_f32_16x16x32_bf16 v[126:129], v[130:133], v[182:185], v[126:129]
	v_mfma_f32_16x16x32_bf16 v[126:129], v[134:137], v[186:189], v[126:129]
	v_mfma_f32_16x16x32_bf16 v[122:125], v[138:141], v[182:185], v[122:125]
	v_mfma_f32_16x16x32_bf16 v[122:125], v[142:145], v[186:189], v[122:125]
	v_mfma_f32_16x16x32_bf16 v[118:121], v[146:149], v[182:185], v[118:121]
	v_mfma_f32_16x16x32_bf16 v[118:121], v[150:153], v[186:189], v[118:121]
	v_mfma_f32_16x16x32_bf16 v[110:113], v[154:157], v[182:185], v[110:113]
	v_mfma_f32_16x16x32_bf16 v[110:113], v[158:161], v[186:189], v[110:113]
	v_mfma_f32_16x16x32_bf16 v[94:97], v[154:157], v[190:193], v[94:97]
	v_mfma_f32_16x16x32_bf16 v[94:97], v[158:161], v[202:205], v[94:97]
	v_mfma_f32_16x16x32_bf16 v[102:105], v[146:149], v[190:193], v[102:105]
	v_mfma_f32_16x16x32_bf16 v[102:105], v[150:153], v[202:205], v[102:105]
	v_mfma_f32_16x16x32_bf16 v[106:109], v[138:141], v[190:193], v[106:109]
	v_mfma_f32_16x16x32_bf16 v[106:109], v[142:145], v[202:205], v[106:109]
	v_mfma_f32_16x16x32_bf16 v[114:117], v[130:133], v[190:193], v[114:117]
	v_mfma_f32_16x16x32_bf16 v[114:117], v[134:137], v[202:205], v[114:117]
	v_mfma_f32_16x16x32_bf16 v[98:101], v[130:133], v[206:209], v[98:101]
	v_mfma_f32_16x16x32_bf16 v[98:101], v[134:137], v[210:213], v[98:101]
	v_mfma_f32_16x16x32_bf16 v[90:93], v[138:141], v[206:209], v[90:93]
	v_mfma_f32_16x16x32_bf16 v[90:93], v[142:145], v[210:213], v[90:93]
	v_mfma_f32_16x16x32_bf16 v[86:89], v[146:149], v[206:209], v[86:89]
	v_mfma_f32_16x16x32_bf16 v[86:89], v[150:153], v[210:213], v[86:89]
	v_mfma_f32_16x16x32_bf16 v[78:81], v[154:157], v[206:209], v[78:81]
	v_mfma_f32_16x16x32_bf16 v[78:81], v[158:161], v[210:213], v[78:81]
	v_mfma_f32_16x16x32_bf16 v[66:69], v[154:157], v[214:217], v[66:69]
	v_mfma_f32_16x16x32_bf16 v[66:69], v[158:161], v[240:243], v[66:69]
	v_mfma_f32_16x16x32_bf16 v[70:73], v[146:149], v[214:217], v[70:73]
	v_mfma_f32_16x16x32_bf16 v[70:73], v[150:153], v[240:243], v[70:73]
	v_mfma_f32_16x16x32_bf16 v[74:77], v[138:141], v[214:217], v[74:77]
	v_mfma_f32_16x16x32_bf16 v[74:77], v[142:145], v[240:243], v[74:77]
	v_mfma_f32_16x16x32_bf16 v[82:85], v[130:133], v[214:217], v[82:85]
	v_mfma_f32_16x16x32_bf16 v[82:85], v[134:137], v[240:243], v[82:85]
	s_setprio 0
	s_barrier
	ds_read_b128 v[182:185], v180 offset:49152
	ds_read_b128 v[186:189], v180 offset:50176
	ds_read_b128 v[190:193], v180 offset:51200
	ds_read_b128 v[202:205], v180 offset:52224
	ds_read_b128 v[206:209], v180 offset:53248
	ds_read_b128 v[210:213], v180 offset:54272
	ds_read_b128 v[214:217], v180 offset:55296
	ds_read_b128 v[240:243], v180 offset:56320
	s_add_u32 s58, s58, 0x80
	s_addc_u32 s59, s59, 0
	s_mov_b32 m0, s89
	s_nop 0
	global_load_lds_dwordx4 v167, s[58:59]
	s_add_u32 s44, s44, 0x80
	s_mov_b32 m0, s95
	s_nop 0
	global_load_lds_dwordx4 v175, s[58:59]
	s_addc_u32 s45, s45, 0
	s_mov_b32 m0, s26
	s_nop 0
	global_load_lds_dwordx4 v167, s[44:45]
	s_nop 0
	s_mov_b32 m0, s27
	s_nop 0
	global_load_lds_dwordx4 v175, s[44:45]
	s_nop 0
	s_mov_b32 m0, s36
	s_nop 0
	global_load_lds_dwordx4 v165, s[56:57]
	s_nop 0
	s_mov_b32 m0, s37
	s_nop 0
	global_load_lds_dwordx4 v171, s[56:57]
	s_waitcnt vmcnt(8)
	s_waitcnt lgkmcnt(0)
	s_barrier
	s_setprio 1
	s_waitcnt lgkmcnt(0)
	v_mfma_f32_16x16x32_bf16 v[62:65], v[130:133], v[182:185], v[62:65]
	v_mfma_f32_16x16x32_bf16 v[62:65], v[134:137], v[186:189], v[62:65]
	v_mfma_f32_16x16x32_bf16 v[58:61], v[138:141], v[182:185], v[58:61]
	v_mfma_f32_16x16x32_bf16 v[58:61], v[142:145], v[186:189], v[58:61]
	v_mfma_f32_16x16x32_bf16 v[54:57], v[146:149], v[182:185], v[54:57]
	v_mfma_f32_16x16x32_bf16 v[54:57], v[150:153], v[186:189], v[54:57]
	v_mfma_f32_16x16x32_bf16 v[50:53], v[154:157], v[182:185], v[50:53]
	v_mfma_f32_16x16x32_bf16 v[50:53], v[158:161], v[186:189], v[50:53]
	v_mfma_f32_16x16x32_bf16 v[30:33], v[154:157], v[190:193], v[30:33]
	v_mfma_f32_16x16x32_bf16 v[30:33], v[158:161], v[202:205], v[30:33]
	v_mfma_f32_16x16x32_bf16 v[38:41], v[146:149], v[190:193], v[38:41]
	v_mfma_f32_16x16x32_bf16 v[38:41], v[150:153], v[202:205], v[38:41]
	v_mfma_f32_16x16x32_bf16 v[42:45], v[138:141], v[190:193], v[42:45]
	v_mfma_f32_16x16x32_bf16 v[42:45], v[142:145], v[202:205], v[42:45]
	v_mfma_f32_16x16x32_bf16 v[46:49], v[130:133], v[190:193], v[46:49]
	v_mfma_f32_16x16x32_bf16 v[46:49], v[134:137], v[202:205], v[46:49]
	v_mfma_f32_16x16x32_bf16 v[34:37], v[130:133], v[206:209], v[34:37]
	v_mfma_f32_16x16x32_bf16 v[34:37], v[134:137], v[210:213], v[34:37]
	v_mfma_f32_16x16x32_bf16 v[26:29], v[138:141], v[206:209], v[26:29]
	v_mfma_f32_16x16x32_bf16 v[26:29], v[142:145], v[210:213], v[26:29]
	v_mfma_f32_16x16x32_bf16 v[22:25], v[146:149], v[206:209], v[22:25]
	v_mfma_f32_16x16x32_bf16 v[22:25], v[150:153], v[210:213], v[22:25]
	v_mfma_f32_16x16x32_bf16 v[14:17], v[154:157], v[206:209], v[14:17]
	v_mfma_f32_16x16x32_bf16 v[14:17], v[158:161], v[210:213], v[14:17]
	v_mfma_f32_16x16x32_bf16 v[2:5], v[154:157], v[214:217], v[2:5]
	v_mfma_f32_16x16x32_bf16 v[2:5], v[158:161], v[240:243], v[2:5]
	v_mfma_f32_16x16x32_bf16 v[6:9], v[146:149], v[214:217], v[6:9]
	v_mfma_f32_16x16x32_bf16 v[6:9], v[150:153], v[240:243], v[6:9]
	v_mfma_f32_16x16x32_bf16 v[10:13], v[138:141], v[214:217], v[10:13]
	v_mfma_f32_16x16x32_bf16 v[10:13], v[142:145], v[240:243], v[10:13]
	v_mfma_f32_16x16x32_bf16 v[18:21], v[130:133], v[214:217], v[18:21]
	v_mfma_f32_16x16x32_bf16 v[18:21], v[134:137], v[240:243], v[18:21]
	s_setprio 0
	s_barrier
	s_add_u32 s4, s4, 0x100
	s_addc_u32 s5, s5, 0
	s_add_u32 s0, s0, 0x100
	s_addc_u32 s1, s1, 0
	s_cmp_ge_u32 s55, s31
	s_mov_b32 s44, s55

; #define PG8_STAGE(bufoff, gbase, voff) do { _Pragma("unroll") for (int _i = 0; _i < 2; ++_i) { \
;         const unsigned _m0 = ldsb + (unsigned)((bufoff) + _i * 8192); const char* _gb = (const char*)(gbase); \
;         asm volatile("s_mov_b32 m0, %0\n\ts_nop 0\n\tglobal_load_lds_dwordx4 %1, %2" :: "s"(_m0), "v"((voff)[_i]), "s"(_gb) : "m0", "memory"); } } while (0)
; #define PG8_LDA(dst, b, h) do { _Pragma("unroll") for (int m = 0; m < 4; ++m) _Pragma("unroll") for (int k = 0; k < 2; ++k) dst[m][k] = *(const LAS bf16x8*)(lds + PG8_SA(b, h) + aoff + m * 2048 + k * 1024); } while (0)
; #define PG8_LDB(dst, b, h) do { _Pragma("unroll") for (int n = 0; n < 2; ++n) _Pragma("unroll") for (int k = 0; k < 2; ++k) dst[n][k] = *(const LAS bf16x8*)(lds + PG8_SB(b, h) + boff + n * 2048 + k * 1024); } while (0)
; #define PG8_MMA(ai, bj, At, Bt) do { __builtin_amdgcn_s_setprio(1); _Pragma("unroll") for (int m = 0; m < 4; ++m) _Pragma("unroll") for (int n = 0; n < 2; ++n) _Pragma("unroll") for (int k = 0; k < 2; ++k) \
;         acc[ai][bj][m][n] = __builtin_amdgcn_mfma_f32_16x16x32_bf16(Bt[n][k], At[m][k], acc[ai][bj][m][n], 0, 0, 0); __builtin_amdgcn_s_setprio(0); } while (0)
; #define PG8_WAIT_V(n) asm volatile("s_waitcnt vmcnt(" #n ")" ::: "memory")
; #define PG8_WAIT_L(n) asm volatile("s_waitcnt lgkmcnt(" #n ")" ::: "memory")
; #define PG8_BAR __builtin_amdgcn_s_barrier()
; #define PG8_SCHED __builtin_amdgcn_sched_barrier(0)
;     __device__ bool next(int i, Unit& u) const {
;         const long L = (long)i * G + c; if (L >= nwg) return false;
;         int wgid = (int)L; { const int q = nwg / NXCD, r = nwg % NXCD, xcd = wgid % NXCD, off = wgid / NXCD; wgid = (xcd < r ? xcd * (q + 1) : r * (q + 1) + (xcd - r) * q) + off; }
;         const int nig = WGM * nN, gid = wgid / nig, fm = gid * WGM, gsz = (nM - fm) < WGM ? (nM - fm) : WGM;
;         u.pm = fm + ((wgid % nig) % gsz); u.pn = (wgid % nig) / gsz; return true;
; template <class Epi, bool ALIGN_EPI>
; __device__ __forceinline__ void gemm_phase(LAS unsigned char* lds, const Gemm g, const StaticOrder& S, const Epi& E) {
;     ...
;             PG8_LDB(B0, 0, 0); PG8_LDB(B1, 0, 1); PG8_SCHED; PG8_LDA(At, 0, 0); PG8_STAGE(PG8_SA(1, 1), a1 + hstepA, voffA);
;             PG8_WAIT_V(8); PG8_WAIT_L(0); PG8_BAR; PG8_MMA(0, 0, At, B0); PG8_MMA(0, 1, At, B1); PG8_BAR; PG8_SCHED;
.LBB0_303:
	v_add_u32_e32 v134, 0x10000, v185
	v_add_u32_e32 v158, 0x14000, v185
	ds_read_b128 v[74:77], v134
	ds_read_b128 v[94:97], v134 offset:1024
	ds_read_b128 v[114:117], v134 offset:2048
	ds_read_b128 v[134:137], v134 offset:3072
	ds_read_b128 v[146:149], v158
	ds_read_b128 v[150:153], v158 offset:1024
	ds_read_b128 v[154:157], v158 offset:2048
	ds_read_b128 v[158:161], v158 offset:3072
	ds_read_b128 v[162:165], v186
	ds_read_b128 v[166:169], v186 offset:1024
	ds_read_b128 v[170:173], v186 offset:2048
	ds_read_b128 v[174:177], v186 offset:3072
	ds_read_b128 v[188:191], v186 offset:4096
	ds_read_b128 v[202:205], v186 offset:5120
	ds_read_b128 v[206:209], v186 offset:6144
	ds_read_b128 v[210:213], v186 offset:7168
	s_add_i32 s85, s85, 1
	s_mul_i32 s4, s85, s27
	s_mul_hi_u32 s5, s85, s87
	s_add_i32 s5, s5, s4
	s_mul_i32 s4, s85, s87
	s_add_u32 s4, s4, s16
	s_addc_u32 s5, s5, s68
	v_mov_b64_e32 v[2:3], s[46:47]
	v_cmp_ge_i64_e32 vcc, s[4:5], v[2:3]
	v_cmp_lt_i64_e64 s[8:9], s[4:5], v[2:3]
	s_cbranch_vccnz .LBB0_305
	s_ashr_i32 s5, s4, 31
	s_lshr_b32 s5, s5, 29
	s_add_i32 s5, s4, s5
	s_ashr_i32 s30, s5, 3
	s_and_b32 s5, s5, -8
	s_sub_i32 s4, s4, s5
	s_lshr_b32 s5, s4, 31
	s_or_b32 s5, s78, s5
	s_mul_i32 s4, s5, s4
	s_add_i32 s4, s4, s30
	s_abs_i32 s30, s4
	v_readlane_b32 s31, v254, 48
	s_mul_hi_u32 s31, s30, s31
	s_mul_i32 s34, s31, s26
	s_sub_i32 s30, s30, s34
	s_ashr_i32 s5, s4, 31
	s_add_i32 s34, s31, 1
	s_sub_i32 s35, s30, s26
	s_cmp_ge_u32 s30, s26
	s_cselect_b32 s31, s34, s31
	s_cselect_b32 s30, s35, s30
	s_add_i32 s34, s31, 1
	s_cmp_ge_u32 s30, s26
	s_cselect_b32 s30, s34, s31
	s_xor_b32 s30, s30, s5
	s_sub_i32 s5, s30, s5
	s_lshl_b32 s30, s5, 3
	s_sub_i32 s31, 0x80, s30
	s_min_i32 s31, s31, 8
	s_abs_i32 s34, s31
	v_cvt_f32_u32_e32 v2, s34
	s_sub_i32 s36, 0, s34
	s_mul_i32 s5, s5, s26
	s_sub_i32 s4, s4, s5
	v_rcp_iflag_f32_e32 v2, v2
	s_abs_i32 s35, s4
	s_xor_b32 s5, s4, s31
	s_ashr_i32 s5, s5, 31
	v_mul_f32_e32 v2, 0x4f7ffffe, v2
	v_cvt_u32_f32_e32 v2, v2
	s_nop 0
	v_readfirstlane_b32 s37, v2
	s_mul_i32 s36, s36, s37
	s_mul_hi_u32 s36, s37, s36
	s_add_i32 s37, s37, s36
	s_mul_hi_u32 s36, s35, s37
	s_mul_i32 s37, s36, s34
	s_sub_i32 s35, s35, s37
	s_add_i32 s37, s36, 1
	s_sub_i32 s38, s35, s34
	s_cmp_ge_u32 s35, s34
	s_cselect_b32 s36, s37, s36
	s_cselect_b32 s35, s38, s35
	s_add_i32 s37, s36, 1
	s_cmp_ge_u32 s35, s34
	s_cselect_b32 s34, s37, s36
	s_xor_b32 s34, s34, s5
	s_sub_i32 s34, s34, s5
	s_mul_i32 s5, s34, s31
	s_sub_i32 s4, s4, s5
	s_add_i32 s36, s4, s30
.LBB0_305:
	s_ashr_i32 s37, s36, 31
	s_lshl_b64 s[4:5], s[36:37], 19
	s_add_u32 s38, s18, s4
	s_addc_u32 s39, s19, s5
	s_and_b64 s[4:5], s[8:9], exec
	s_cselect_b32 s4, s39, s59
	s_cselect_b32 s5, s38, s58
	s_ashr_i32 s35, s34, 31
	s_lshl_b64 s[50:51], s[34:35], 19
	s_add_u32 s90, s1, s50
	s_addc_u32 s91, s14, s51
	s_and_b64 s[50:51], s[8:9], exec
	s_cselect_b32 s35, s91, s57
	s_cselect_b32 s37, s90, s56
	s_add_u32 s41, s56, 0x100
	s_addc_u32 s49, s57, 0
	s_add_u32 s92, s58, 0x40080
	s_addc_u32 s93, s59, 0
	s_mov_b32 s50, -2
	s_add_u32 s30, s92, 0xfffc0080
	s_addc_u32 s31, s93, -1
	s_cmp_eq_u32 s50, 12
	s_cselect_b32 s60, s5, s30
	s_cselect_b32 s61, s4, s31
	s_cselect_b32 s58, s37, s41
	s_cselect_b32 s59, s35, s49
	s_add_u32 s56, s60, 0x80
	s_addc_u32 s57, s61, 0
	s_mov_b32 m0, s67
	s_nop 0
	global_load_lds_dwordx4 v0, s[92:93]
	s_nop 0
	s_mov_b32 m0, s65
	s_nop 0
	global_load_lds_dwordx4 v181, s[92:93]
	s_waitcnt vmcnt(8)
	s_waitcnt lgkmcnt(0)
	s_barrier
	s_setprio 1
	s_waitcnt lgkmcnt(0)
	v_mfma_f32_16x16x32_bf16 v[142:145], v[74:77], v[162:165], 0
	v_mfma_f32_16x16x32_bf16 v[142:145], v[94:97], v[166:169], v[142:145]
	v_mfma_f32_16x16x32_bf16 v[138:141], v[114:117], v[162:165], 0
	v_mfma_f32_16x16x32_bf16 v[138:141], v[134:137], v[166:169], v[138:141]
	v_mfma_f32_16x16x32_bf16 v[130:133], v[146:149], v[162:165], 0
	v_mfma_f32_16x16x32_bf16 v[130:133], v[150:153], v[166:169], v[130:133]
	v_mfma_f32_16x16x32_bf16 v[126:129], v[154:157], v[162:165], 0
	v_mfma_f32_16x16x32_bf16 v[126:129], v[158:161], v[166:169], v[126:129]
	v_mfma_f32_16x16x32_bf16 v[106:109], v[154:157], v[170:173], 0
	v_mfma_f32_16x16x32_bf16 v[106:109], v[158:161], v[174:177], v[106:109]
	v_mfma_f32_16x16x32_bf16 v[110:113], v[146:149], v[170:173], 0
	v_mfma_f32_16x16x32_bf16 v[110:113], v[150:153], v[174:177], v[110:113]
	v_mfma_f32_16x16x32_bf16 v[118:121], v[114:117], v[170:173], 0
	v_mfma_f32_16x16x32_bf16 v[118:121], v[134:137], v[174:177], v[118:121]
	v_mfma_f32_16x16x32_bf16 v[122:125], v[74:77], v[170:173], 0
	v_mfma_f32_16x16x32_bf16 v[122:125], v[94:97], v[174:177], v[122:125]
	v_mfma_f32_16x16x32_bf16 v[102:105], v[74:77], v[188:191], 0
	v_mfma_f32_16x16x32_bf16 v[102:105], v[94:97], v[202:205], v[102:105]
	v_mfma_f32_16x16x32_bf16 v[98:101], v[114:117], v[188:191], 0
	v_mfma_f32_16x16x32_bf16 v[98:101], v[134:137], v[202:205], v[98:101]
	v_mfma_f32_16x16x32_bf16 v[90:93], v[146:149], v[188:191], 0
	v_mfma_f32_16x16x32_bf16 v[90:93], v[150:153], v[202:205], v[90:93]
	v_mfma_f32_16x16x32_bf16 v[86:89], v[154:157], v[188:191], 0
	v_mfma_f32_16x16x32_bf16 v[86:89], v[158:161], v[202:205], v[86:89]
	v_mfma_f32_16x16x32_bf16 v[66:69], v[154:157], v[206:209], 0
	v_mfma_f32_16x16x32_bf16 v[66:69], v[158:161], v[210:213], v[66:69]
	v_mfma_f32_16x16x32_bf16 v[70:73], v[146:149], v[206:209], 0
	v_mfma_f32_16x16x32_bf16 v[70:73], v[150:153], v[210:213], v[70:73]
	v_mfma_f32_16x16x32_bf16 v[78:81], v[114:117], v[206:209], 0
	v_mfma_f32_16x16x32_bf16 v[78:81], v[134:137], v[210:213], v[78:81]
	v_mfma_f32_16x16x32_bf16 v[82:85], v[74:77], v[206:209], 0
	v_mfma_f32_16x16x32_bf16 v[82:85], v[94:97], v[210:213], v[82:85]
	s_setprio 0
	s_barrier
; #define PG8_STAGE(bufoff, gbase, voff) do { _Pragma("unroll") for (int _i = 0; _i < 2; ++_i) { \
;         const unsigned _m0 = ldsb + (unsigned)((bufoff) + _i * 8192); const char* _gb = (const char*)(gbase); \
;         asm volatile("s_mov_b32 m0, %0\n\ts_nop 0\n\tglobal_load_lds_dwordx4 %1, %2" :: "s"(_m0), "v"((voff)[_i]), "s"(_gb) : "m0", "memory"); } } while (0)
; #define PG8_LDA(dst, b, h) do { _Pragma("unroll") for (int m = 0; m < 4; ++m) _Pragma("unroll") for (int k = 0; k < 2; ++k) dst[m][k] = *(const LAS bf16x8*)(lds + PG8_SA(b, h) + aoff + m * 2048 + k * 1024); } while (0)
; #define PG8_LDB(dst, b, h) do { _Pragma("unroll") for (int n = 0; n < 2; ++n) _Pragma("unroll") for (int k = 0; k < 2; ++k) dst[n][k] = *(const LAS bf16x8*)(lds + PG8_SB(b, h) + boff + n * 2048 + k * 1024); } while (0)
; #define PG8_MMA(ai, bj, At, Bt) do { __builtin_amdgcn_s_setprio(1); _Pragma("unroll") for (int m = 0; m < 4; ++m) _Pragma("unroll") for (int n = 0; n < 2; ++n) _Pragma("unroll") for (int k = 0; k < 2; ++k) \
;         acc[ai][bj][m][n] = __builtin_amdgcn_mfma_f32_16x16x32_bf16(Bt[n][k], At[m][k], acc[ai][bj][m][n], 0, 0, 0); __builtin_amdgcn_s_setprio(0); } while (0)
; #define PG8_WAIT_V(n) asm volatile("s_waitcnt vmcnt(" #n ")" ::: "memory")
; #define PG8_WAIT_L(n) asm volatile("s_waitcnt lgkmcnt(" #n ")" ::: "memory")
; #define PG8_BAR __builtin_amdgcn_s_barrier()
; #define PG8_SCHED __builtin_amdgcn_sched_barrier(0)
; template <class Epi, bool ALIGN_EPI>
; __device__ __forceinline__ void gemm_phase(LAS unsigned char* lds, const Gemm g, const StaticOrder& S, const Epi& E) {
;     ...
;             PG8_LDA(At, 0, 1); PG8_STAGE(PG8_SB(0, 0), b2, voffB); PG8_STAGE(PG8_SB(0, 1), b2 + hstepB, voffB); PG8_STAGE(PG8_SA(0, 0), a2, voffA);
;             PG8_WAIT_V(8); PG8_WAIT_L(0); PG8_BAR; PG8_MMA(1, 0, At, B0); PG8_MMA(1, 1, At, B1); PG8_BAR; PG8_SCHED;
;             PG8_LDB(B0, 1, 0); PG8_LDB(B1, 1, 1); PG8_SCHED; PG8_LDA(At, 1, 0); PG8_STAGE(PG8_SA(0, 1), a2 + hstepA, voffA);
;             PG8_WAIT_V(8); PG8_WAIT_L(0); PG8_BAR; PG8_MMA(0, 0, At, B0); PG8_MMA(0, 1, At, B1); PG8_BAR; PG8_SCHED;
	ds_read_b128 v[162:165], v186 offset:16384
	ds_read_b128 v[166:169], v186 offset:17408
	ds_read_b128 v[170:173], v186 offset:18432
	ds_read_b128 v[174:177], v186 offset:19456
	ds_read_b128 v[188:191], v186 offset:20480
	ds_read_b128 v[202:205], v186 offset:21504
	ds_read_b128 v[206:209], v186 offset:22528
	ds_read_b128 v[210:213], v186 offset:23552
	s_mov_b32 m0, s29
	s_nop 0
	global_load_lds_dwordx4 v180, s[58:59]
	s_add_u32 s30, s58, 0x40000
	s_mov_b32 m0, s42
	s_nop 0
	global_load_lds_dwordx4 v182, s[58:59]
	s_addc_u32 s31, s59, 0
	s_mov_b32 m0, s43
	s_nop 0
	global_load_lds_dwordx4 v180, s[30:31]
	s_nop 0
	s_mov_b32 m0, s44
	s_nop 0
	global_load_lds_dwordx4 v182, s[30:31]
	s_nop 0
	s_mov_b32 m0, s15
	s_nop 0
	global_load_lds_dwordx4 v0, s[60:61]
	s_nop 0
	s_mov_b32 m0, s45
	s_nop 0
	global_load_lds_dwordx4 v181, s[60:61]
	s_waitcnt vmcnt(8)
	s_waitcnt lgkmcnt(0)
	s_barrier
	s_setprio 1
	s_waitcnt lgkmcnt(0)
	v_mfma_f32_16x16x32_bf16 v[62:65], v[74:77], v[162:165], 0
	v_mfma_f32_16x16x32_bf16 v[62:65], v[94:97], v[166:169], v[62:65]
	v_mfma_f32_16x16x32_bf16 v[58:61], v[114:117], v[162:165], 0
	v_mfma_f32_16x16x32_bf16 v[58:61], v[134:137], v[166:169], v[58:61]
	v_mfma_f32_16x16x32_bf16 v[54:57], v[146:149], v[162:165], 0
	v_mfma_f32_16x16x32_bf16 v[54:57], v[150:153], v[166:169], v[54:57]
	v_mfma_f32_16x16x32_bf16 v[50:53], v[154:157], v[162:165], 0
	v_mfma_f32_16x16x32_bf16 v[50:53], v[158:161], v[166:169], v[50:53]
	v_mfma_f32_16x16x32_bf16 v[34:37], v[154:157], v[170:173], 0
	v_mfma_f32_16x16x32_bf16 v[34:37], v[158:161], v[174:177], v[34:37]
	v_mfma_f32_16x16x32_bf16 v[38:41], v[146:149], v[170:173], 0
	v_mfma_f32_16x16x32_bf16 v[38:41], v[150:153], v[174:177], v[38:41]
	v_mfma_f32_16x16x32_bf16 v[42:45], v[114:117], v[170:173], 0
	v_mfma_f32_16x16x32_bf16 v[42:45], v[134:137], v[174:177], v[42:45]
	v_mfma_f32_16x16x32_bf16 v[46:49], v[74:77], v[170:173], 0
	v_mfma_f32_16x16x32_bf16 v[46:49], v[94:97], v[174:177], v[46:49]
	v_mfma_f32_16x16x32_bf16 v[30:33], v[74:77], v[188:191], 0
	v_mfma_f32_16x16x32_bf16 v[30:33], v[94:97], v[202:205], v[30:33]
	v_mfma_f32_16x16x32_bf16 v[26:29], v[114:117], v[188:191], 0
	v_mfma_f32_16x16x32_bf16 v[26:29], v[134:137], v[202:205], v[26:29]
	v_mfma_f32_16x16x32_bf16 v[22:25], v[146:149], v[188:191], 0
	v_mfma_f32_16x16x32_bf16 v[22:25], v[150:153], v[202:205], v[22:25]
	v_mfma_f32_16x16x32_bf16 v[18:21], v[154:157], v[188:191], 0
	v_mfma_f32_16x16x32_bf16 v[18:21], v[158:161], v[202:205], v[18:21]
	v_mfma_f32_16x16x32_bf16 v[2:5], v[154:157], v[206:209], 0
	v_mfma_f32_16x16x32_bf16 v[2:5], v[158:161], v[210:213], v[2:5]
	v_mfma_f32_16x16x32_bf16 v[6:9], v[146:149], v[206:209], 0
	v_mfma_f32_16x16x32_bf16 v[6:9], v[150:153], v[210:213], v[6:9]
	v_mfma_f32_16x16x32_bf16 v[10:13], v[114:117], v[206:209], 0
	v_mfma_f32_16x16x32_bf16 v[10:13], v[134:137], v[210:213], v[10:13]
	v_mfma_f32_16x16x32_bf16 v[14:17], v[74:77], v[206:209], 0
	v_mfma_f32_16x16x32_bf16 v[14:17], v[94:97], v[210:213], v[14:17]
	s_setprio 0
	s_barrier
	v_add_u32_e32 v134, 0x18000, v185
	v_add_u32_e32 v158, 0x1c000, v185
	ds_read_b128 v[74:77], v134
	ds_read_b128 v[94:97], v134 offset:1024
	ds_read_b128 v[114:117], v134 offset:2048
	ds_read_b128 v[134:137], v134 offset:3072
	ds_read_b128 v[146:149], v158
	ds_read_b128 v[150:153], v158 offset:1024
	ds_read_b128 v[154:157], v158 offset:2048
	ds_read_b128 v[158:161], v158 offset:3072
	ds_read_b128 v[162:165], v186 offset:32768
	ds_read_b128 v[166:169], v186 offset:33792
	ds_read_b128 v[170:173], v186 offset:34816
	ds_read_b128 v[174:177], v186 offset:35840
	ds_read_b128 v[188:191], v186 offset:36864
	ds_read_b128 v[202:205], v186 offset:37888
	ds_read_b128 v[206:209], v186 offset:38912
	ds_read_b128 v[210:213], v186 offset:39936
	s_add_u32 s30, s60, 0x40000
	s_addc_u32 s31, s61, 0
	s_mov_b32 m0, s55
	s_nop 0
	global_load_lds_dwordx4 v0, s[30:31]
	s_nop 0
	s_mov_b32 m0, s88
	s_nop 0
	global_load_lds_dwordx4 v181, s[30:31]
	s_waitcnt vmcnt(8)
	s_waitcnt lgkmcnt(0)
	s_barrier
; #define PG8_STAGE(bufoff, gbase, voff) do { _Pragma("unroll") for (int _i = 0; _i < 2; ++_i) { \
;         const unsigned _m0 = ldsb + (unsigned)((bufoff) + _i * 8192); const char* _gb = (const char*)(gbase); \
;         asm volatile("s_mov_b32 m0, %0\n\ts_nop 0\n\tglobal_load_lds_dwordx4 %1, %2" :: "s"(_m0), "v"((voff)[_i]), "s"(_gb) : "m0", "memory"); } } while (0)
; #define PG8_LDA(dst, b, h) do { _Pragma("unroll") for (int m = 0; m < 4; ++m) _Pragma("unroll") for (int k = 0; k < 2; ++k) dst[m][k] = *(const LAS bf16x8*)(lds + PG8_SA(b, h) + aoff + m * 2048 + k * 1024); } while (0)
; #define PG8_MMA(ai, bj, At, Bt) do { __builtin_amdgcn_s_setprio(1); _Pragma("unroll") for (int m = 0; m < 4; ++m) _Pragma("unroll") for (int n = 0; n < 2; ++n) _Pragma("unroll") for (int k = 0; k < 2; ++k) \
;         acc[ai][bj][m][n] = __builtin_amdgcn_mfma_f32_16x16x32_bf16(Bt[n][k], At[m][k], acc[ai][bj][m][n], 0, 0, 0); __builtin_amdgcn_s_setprio(0); } while (0)
; #define PG8_WAIT_V(n) asm volatile("s_waitcnt vmcnt(" #n ")" ::: "memory")
; #define PG8_WAIT_L(n) asm volatile("s_waitcnt lgkmcnt(" #n ")" ::: "memory")
; #define PG8_BAR __builtin_amdgcn_s_barrier()
; #define PG8_SCHED __builtin_amdgcn_sched_barrier(0)
; template <class Epi, bool ALIGN_EPI>
; __device__ __forceinline__ void gemm_phase(LAS unsigned char* lds, const Gemm g, const StaticOrder& S, const Epi& E) {
;     ...
;             PG8_WAIT_V(8); PG8_WAIT_L(0); PG8_BAR; PG8_MMA(0, 0, At, B0); PG8_MMA(0, 1, At, B1); PG8_BAR; PG8_SCHED;
;             PG8_LDA(At, 1, 1); PG8_STAGE(PG8_SB(1, 0), b3, voffB); PG8_STAGE(PG8_SB(1, 1), b3 + hstepB, voffB); PG8_STAGE(PG8_SA(1, 0), a3, voffA);
;             PG8_WAIT_V(8); PG8_WAIT_L(0); PG8_BAR; PG8_MMA(1, 0, At, B0); PG8_MMA(1, 1, At, B1); PG8_BAR; PG8_SCHED;
;         }
	s_setprio 1
	s_waitcnt lgkmcnt(0)
	v_mfma_f32_16x16x32_bf16 v[142:145], v[74:77], v[162:165], v[142:145]
	v_mfma_f32_16x16x32_bf16 v[142:145], v[94:97], v[166:169], v[142:145]
	v_mfma_f32_16x16x32_bf16 v[138:141], v[114:117], v[162:165], v[138:141]
	v_mfma_f32_16x16x32_bf16 v[138:141], v[134:137], v[166:169], v[138:141]
	v_mfma_f32_16x16x32_bf16 v[130:133], v[146:149], v[162:165], v[130:133]
	v_mfma_f32_16x16x32_bf16 v[130:133], v[150:153], v[166:169], v[130:133]
	v_mfma_f32_16x16x32_bf16 v[126:129], v[154:157], v[162:165], v[126:129]
	v_mfma_f32_16x16x32_bf16 v[126:129], v[158:161], v[166:169], v[126:129]
	v_mfma_f32_16x16x32_bf16 v[106:109], v[154:157], v[170:173], v[106:109]
	v_mfma_f32_16x16x32_bf16 v[106:109], v[158:161], v[174:177], v[106:109]
	v_mfma_f32_16x16x32_bf16 v[110:113], v[146:149], v[170:173], v[110:113]
	v_mfma_f32_16x16x32_bf16 v[110:113], v[150:153], v[174:177], v[110:113]
	v_mfma_f32_16x16x32_bf16 v[118:121], v[114:117], v[170:173], v[118:121]
	v_mfma_f32_16x16x32_bf16 v[118:121], v[134:137], v[174:177], v[118:121]
	v_mfma_f32_16x16x32_bf16 v[122:125], v[74:77], v[170:173], v[122:125]
	v_mfma_f32_16x16x32_bf16 v[122:125], v[94:97], v[174:177], v[122:125]
	v_mfma_f32_16x16x32_bf16 v[102:105], v[74:77], v[188:191], v[102:105]
	v_mfma_f32_16x16x32_bf16 v[102:105], v[94:97], v[202:205], v[102:105]
	v_mfma_f32_16x16x32_bf16 v[98:101], v[114:117], v[188:191], v[98:101]
	v_mfma_f32_16x16x32_bf16 v[98:101], v[134:137], v[202:205], v[98:101]
	v_mfma_f32_16x16x32_bf16 v[90:93], v[146:149], v[188:191], v[90:93]
	v_mfma_f32_16x16x32_bf16 v[90:93], v[150:153], v[202:205], v[90:93]
	v_mfma_f32_16x16x32_bf16 v[86:89], v[154:157], v[188:191], v[86:89]
	v_mfma_f32_16x16x32_bf16 v[86:89], v[158:161], v[202:205], v[86:89]
	v_mfma_f32_16x16x32_bf16 v[66:69], v[154:157], v[206:209], v[66:69]
	v_mfma_f32_16x16x32_bf16 v[66:69], v[158:161], v[210:213], v[66:69]
	v_mfma_f32_16x16x32_bf16 v[70:73], v[146:149], v[206:209], v[70:73]
	v_mfma_f32_16x16x32_bf16 v[70:73], v[150:153], v[210:213], v[70:73]
	v_mfma_f32_16x16x32_bf16 v[78:81], v[114:117], v[206:209], v[78:81]
	v_mfma_f32_16x16x32_bf16 v[78:81], v[134:137], v[210:213], v[78:81]
	v_mfma_f32_16x16x32_bf16 v[82:85], v[74:77], v[206:209], v[82:85]
	v_mfma_f32_16x16x32_bf16 v[82:85], v[94:97], v[210:213], v[82:85]
	s_setprio 0
	s_barrier
	ds_read_b128 v[162:165], v186 offset:49152
	ds_read_b128 v[166:169], v186 offset:50176
	ds_read_b128 v[170:173], v186 offset:51200
	ds_read_b128 v[174:177], v186 offset:52224
	ds_read_b128 v[188:191], v186 offset:53248
	ds_read_b128 v[202:205], v186 offset:54272
	ds_read_b128 v[206:209], v186 offset:55296
	ds_read_b128 v[210:213], v186 offset:56320
	s_add_u32 s30, s58, 0x80
	s_addc_u32 s31, s59, 0
	s_mov_b32 m0, s94
	s_nop 0
	global_load_lds_dwordx4 v180, s[30:31]
	s_nop 0
	s_mov_b32 m0, s95
	s_nop 0
	global_load_lds_dwordx4 v182, s[30:31]
	s_add_u32 s30, s58, 0x40080
	s_addc_u32 s31, s59, 0
	s_mov_b32 m0, s17
	s_nop 0
	global_load_lds_dwordx4 v180, s[30:31]
	s_nop 0
	s_mov_b32 m0, s53
	s_nop 0
	global_load_lds_dwordx4 v182, s[30:31]
	s_nop 0
	s_mov_b32 m0, s96
	s_nop 0
	global_load_lds_dwordx4 v0, s[56:57]
	s_nop 0
	s_mov_b32 m0, s97
	s_nop 0
	global_load_lds_dwordx4 v181, s[56:57]
	s_waitcnt vmcnt(8)
	s_waitcnt lgkmcnt(0)
	s_barrier
	s_setprio 1
	s_waitcnt lgkmcnt(0)
	v_mfma_f32_16x16x32_bf16 v[62:65], v[74:77], v[162:165], v[62:65]
	v_mfma_f32_16x16x32_bf16 v[62:65], v[94:97], v[166:169], v[62:65]
	v_mfma_f32_16x16x32_bf16 v[58:61], v[114:117], v[162:165], v[58:61]
	v_mfma_f32_16x16x32_bf16 v[58:61], v[134:137], v[166:169], v[58:61]
	v_mfma_f32_16x16x32_bf16 v[54:57], v[146:149], v[162:165], v[54:57]
	v_mfma_f32_16x16x32_bf16 v[54:57], v[150:153], v[166:169], v[54:57]
	v_mfma_f32_16x16x32_bf16 v[50:53], v[154:157], v[162:165], v[50:53]
	v_mfma_f32_16x16x32_bf16 v[50:53], v[158:161], v[166:169], v[50:53]
	v_mfma_f32_16x16x32_bf16 v[34:37], v[154:157], v[170:173], v[34:37]
	v_mfma_f32_16x16x32_bf16 v[34:37], v[158:161], v[174:177], v[34:37]
	v_mfma_f32_16x16x32_bf16 v[38:41], v[146:149], v[170:173], v[38:41]
	v_mfma_f32_16x16x32_bf16 v[38:41], v[150:153], v[174:177], v[38:41]
	v_mfma_f32_16x16x32_bf16 v[42:45], v[114:117], v[170:173], v[42:45]
	v_mfma_f32_16x16x32_bf16 v[42:45], v[134:137], v[174:177], v[42:45]
	v_mfma_f32_16x16x32_bf16 v[46:49], v[74:77], v[170:173], v[46:49]
	v_mfma_f32_16x16x32_bf16 v[46:49], v[94:97], v[174:177], v[46:49]
	v_mfma_f32_16x16x32_bf16 v[30:33], v[74:77], v[188:191], v[30:33]
	v_mfma_f32_16x16x32_bf16 v[30:33], v[94:97], v[202:205], v[30:33]
	v_mfma_f32_16x16x32_bf16 v[26:29], v[114:117], v[188:191], v[26:29]
	v_mfma_f32_16x16x32_bf16 v[26:29], v[134:137], v[202:205], v[26:29]
	v_mfma_f32_16x16x32_bf16 v[22:25], v[146:149], v[188:191], v[22:25]
	v_mfma_f32_16x16x32_bf16 v[22:25], v[150:153], v[202:205], v[22:25]
	v_mfma_f32_16x16x32_bf16 v[18:21], v[154:157], v[188:191], v[18:21]
	v_mfma_f32_16x16x32_bf16 v[18:21], v[158:161], v[202:205], v[18:21]
	v_mfma_f32_16x16x32_bf16 v[2:5], v[154:157], v[206:209], v[2:5]
	v_mfma_f32_16x16x32_bf16 v[2:5], v[158:161], v[210:213], v[2:5]
	v_mfma_f32_16x16x32_bf16 v[6:9], v[146:149], v[206:209], v[6:9]
	v_mfma_f32_16x16x32_bf16 v[6:9], v[150:153], v[210:213], v[6:9]
	v_mfma_f32_16x16x32_bf16 v[10:13], v[114:117], v[206:209], v[10:13]
	v_mfma_f32_16x16x32_bf16 v[10:13], v[134:137], v[210:213], v[10:13]
	v_mfma_f32_16x16x32_bf16 v[14:17], v[74:77], v[206:209], v[14:17]
	v_mfma_f32_16x16x32_bf16 v[14:17], v[94:97], v[210:213], v[14:17]
	s_setprio 0
	s_barrier
	s_add_i32 s50, s50, 2
	s_add_u32 s41, s41, 0x100
	s_addc_u32 s49, s49, 0
	s_add_u32 s92, s92, 0x100
	s_addc_u32 s93, s93, 0
	s_cmp_gt_u32 s50, 13
